# GEMM K-loops: MFMA order within each 8-MFMA group changed to a snake so consecutive MFMAs share one operand register
# speedup vs baseline: 1.0019x; 1.0002x over previous
.LBB0_260:
	v_add_u32_e32 v168, 0x10000, v232
	v_add_u32_e32 v180, 0x14000, v232
	v_lshl_add_u64 v[224:225], v[222:223], 0, s[62:63]
	s_add_i32 m0, s35, 0xc000
	s_waitcnt lgkmcnt(0)
	ds_read_b128 v[148:151], v207
	ds_read_b128 v[164:167], v207 offset:1024
	ds_read_b128 v[144:147], v207 offset:2048
	ds_read_b128 v[160:163], v207 offset:3072
	ds_read_b128 v[140:143], v207 offset:4096
	ds_read_b128 v[156:159], v207 offset:5120
	ds_read_b128 v[136:139], v207 offset:6144
	ds_read_b128 v[152:155], v207 offset:7168
	ds_read_b128 v[184:187], v168
	ds_read_b128 v[188:191], v168 offset:1024
	ds_read_b128 v[192:195], v168 offset:2048
	ds_read_b128 v[196:199], v168 offset:3072
	ds_read_b128 v[168:171], v180
	ds_read_b128 v[172:175], v180 offset:1024
	ds_read_b128 v[176:179], v180 offset:2048
	ds_read_b128 v[180:183], v180 offset:3072
	global_load_lds_dwordx4 v[224:225], off
	v_lshl_add_u64 v[224:225], v[220:221], 0, s[62:63]
	s_add_i32 m0, s35, 0xe000
	s_nop 0
	global_load_lds_dwordx4 v[224:225], off
	s_waitcnt vmcnt(8)
	s_waitcnt lgkmcnt(0)
	s_barrier
	s_setprio 1
	s_waitcnt lgkmcnt(0)
	v_mfma_f32_16x16x32_bf16 v[132:135], v[184:187], v[148:151], v[132:135]
	v_mfma_f32_16x16x32_bf16 v[128:131], v[192:195], v[148:151], v[128:131]
	v_mfma_f32_16x16x32_bf16 v[112:115], v[192:195], v[144:147], v[112:115]
	v_mfma_f32_16x16x32_bf16 v[116:119], v[184:187], v[144:147], v[116:119]
	v_mfma_f32_16x16x32_bf16 v[100:103], v[184:187], v[140:143], v[100:103]
	v_mfma_f32_16x16x32_bf16 v[96:99], v[192:195], v[140:143], v[96:99]
	v_mfma_f32_16x16x32_bf16 v[80:83], v[192:195], v[136:139], v[80:83]
	v_mfma_f32_16x16x32_bf16 v[84:87], v[184:187], v[136:139], v[84:87]
	v_mfma_f32_16x16x32_bf16 v[132:135], v[188:191], v[164:167], v[132:135]
	v_mfma_f32_16x16x32_bf16 v[128:131], v[196:199], v[164:167], v[128:131]
	v_mfma_f32_16x16x32_bf16 v[112:115], v[196:199], v[160:163], v[112:115]
	v_mfma_f32_16x16x32_bf16 v[116:119], v[188:191], v[160:163], v[116:119]
	v_mfma_f32_16x16x32_bf16 v[100:103], v[188:191], v[156:159], v[100:103]
	v_mfma_f32_16x16x32_bf16 v[96:99], v[196:199], v[156:159], v[96:99]
	v_mfma_f32_16x16x32_bf16 v[80:83], v[196:199], v[152:155], v[80:83]
	v_mfma_f32_16x16x32_bf16 v[84:87], v[188:191], v[152:155], v[84:87]
	s_setprio 0
	s_setprio 1
	v_mfma_f32_16x16x32_bf16 v[124:127], v[168:171], v[148:151], v[124:127]
	v_mfma_f32_16x16x32_bf16 v[120:123], v[176:179], v[148:151], v[120:123]
	v_mfma_f32_16x16x32_bf16 v[104:107], v[176:179], v[144:147], v[104:107]
	v_mfma_f32_16x16x32_bf16 v[108:111], v[168:171], v[144:147], v[108:111]
	v_mfma_f32_16x16x32_bf16 v[92:95], v[168:171], v[140:143], v[92:95]
	v_mfma_f32_16x16x32_bf16 v[88:91], v[176:179], v[140:143], v[88:91]
	v_mfma_f32_16x16x32_bf16 v[72:75], v[176:179], v[136:139], v[72:75]
	v_mfma_f32_16x16x32_bf16 v[76:79], v[168:171], v[136:139], v[76:79]
	v_mfma_f32_16x16x32_bf16 v[124:127], v[172:175], v[164:167], v[124:127]
	v_mfma_f32_16x16x32_bf16 v[120:123], v[180:183], v[164:167], v[120:123]
	v_mfma_f32_16x16x32_bf16 v[104:107], v[180:183], v[160:163], v[104:107]
	v_mfma_f32_16x16x32_bf16 v[108:111], v[172:175], v[160:163], v[108:111]
	v_mfma_f32_16x16x32_bf16 v[92:95], v[172:175], v[156:159], v[92:95]
	v_mfma_f32_16x16x32_bf16 v[88:91], v[180:183], v[156:159], v[88:91]
	v_mfma_f32_16x16x32_bf16 v[72:75], v[180:183], v[152:155], v[72:75]
	v_mfma_f32_16x16x32_bf16 v[76:79], v[172:175], v[152:155], v[76:79]
	s_setprio 0
	s_barrier
	v_cndmask_b32_e64 v204, 0, 1, s[60:61]
	v_cmp_ne_u32_e64 s[50:51], 1, v204
	s_andn2_b64 vcc, exec, s[60:61]
	s_cbranch_vccnz .LBB0_262
	ds_read_b128 v[148:151], v207 offset:16384
	ds_read_b128 v[164:167], v207 offset:17408
	ds_read_b128 v[144:147], v207 offset:18432
	ds_read_b128 v[160:163], v207 offset:19456
	ds_read_b128 v[140:143], v207 offset:20480
	ds_read_b128 v[156:159], v207 offset:21504
	ds_read_b128 v[136:139], v207 offset:22528
	ds_read_b128 v[152:155], v207 offset:23552
.LBB0_262:
	s_add_u32 s12, s58, s62
	s_addc_u32 s13, s59, s63
	s_add_u32 s14, s12, 0x100
	s_addc_u32 s15, s13, 0
	s_add_u32 s75, s26, s62
	s_addc_u32 s76, s27, s63
	s_cmpk_eq_i32 s62, 0xf00
	s_cselect_b64 s[52:53], -1, 0
	s_and_b64 s[12:13], s[52:53], exec
	s_cselect_b32 s13, s21, s76
	s_cselect_b32 s12, s73, s75
	s_mov_b32 m0, s38
	s_cselect_b32 s15, s25, s15
	s_cselect_b32 s14, s33, s14
	v_lshl_add_u64 v[224:225], s[12:13], 0, v[208:209]
	s_add_u32 s76, s12, 0x80000
	global_load_lds_dwordx4 v[224:225], off
	v_lshl_add_u64 v[226:227], s[12:13], 0, v[212:213]
	s_mov_b32 m0, s39
	s_addc_u32 s77, s13, 0
	global_load_lds_dwordx4 v[226:227], off
	v_lshl_add_u64 v[228:229], s[76:77], 0, v[208:209]
	s_mov_b32 m0, s40
	v_lshl_add_u64 v[230:231], s[14:15], 0, v[210:211]
	global_load_lds_dwordx4 v[228:229], off
	v_lshl_add_u64 v[228:229], s[76:77], 0, v[212:213]
	s_mov_b32 m0, s41
	s_and_b64 vcc, exec, s[50:51]
	global_load_lds_dwordx4 v[228:229], off
	v_lshl_add_u64 v[228:229], s[14:15], 0, v[4:5]
	s_mov_b32 m0, s35
	s_nop 0
	global_load_lds_dwordx4 v[228:229], off
	s_mov_b32 m0, s43
	s_nop 0
	global_load_lds_dwordx4 v[230:231], off
	s_waitcnt vmcnt(8)
	s_waitcnt lgkmcnt(0)
	s_barrier
	s_cbranch_vccnz .LBB0_264
	s_setprio 1
	s_waitcnt lgkmcnt(0)
	v_mfma_f32_16x16x32_bf16 v[68:71], v[184:187], v[148:151], v[68:71]
	v_mfma_f32_16x16x32_bf16 v[64:67], v[192:195], v[148:151], v[64:67]
	v_mfma_f32_16x16x32_bf16 v[48:51], v[192:195], v[144:147], v[48:51]
	v_mfma_f32_16x16x32_bf16 v[52:55], v[184:187], v[144:147], v[52:55]
	v_mfma_f32_16x16x32_bf16 v[36:39], v[184:187], v[140:143], v[36:39]
	v_mfma_f32_16x16x32_bf16 v[32:35], v[192:195], v[140:143], v[32:35]
	v_mfma_f32_16x16x32_bf16 v[16:19], v[192:195], v[136:139], v[16:19]
	v_mfma_f32_16x16x32_bf16 v[20:23], v[184:187], v[136:139], v[20:23]
	v_mfma_f32_16x16x32_bf16 v[68:71], v[188:191], v[164:167], v[68:71]
	v_mfma_f32_16x16x32_bf16 v[64:67], v[196:199], v[164:167], v[64:67]
	v_mfma_f32_16x16x32_bf16 v[48:51], v[196:199], v[160:163], v[48:51]
	v_mfma_f32_16x16x32_bf16 v[52:55], v[188:191], v[160:163], v[52:55]
	v_mfma_f32_16x16x32_bf16 v[36:39], v[188:191], v[156:159], v[36:39]
	v_mfma_f32_16x16x32_bf16 v[32:35], v[196:199], v[156:159], v[32:35]
	v_mfma_f32_16x16x32_bf16 v[16:19], v[196:199], v[152:155], v[16:19]
	v_mfma_f32_16x16x32_bf16 v[20:23], v[188:191], v[152:155], v[20:23]
	s_setprio 0
	s_setprio 1
	v_mfma_f32_16x16x32_bf16 v[60:63], v[168:171], v[148:151], v[60:63]
	v_mfma_f32_16x16x32_bf16 v[56:59], v[176:179], v[148:151], v[56:59]
	v_mfma_f32_16x16x32_bf16 v[40:43], v[176:179], v[144:147], v[40:43]
	v_mfma_f32_16x16x32_bf16 v[44:47], v[168:171], v[144:147], v[44:47]
	v_mfma_f32_16x16x32_bf16 v[28:31], v[168:171], v[140:143], v[28:31]
	v_mfma_f32_16x16x32_bf16 v[24:27], v[176:179], v[140:143], v[24:27]
	v_mfma_f32_16x16x32_bf16 v[8:11], v[176:179], v[136:139], v[8:11]
	v_mfma_f32_16x16x32_bf16 v[12:15], v[168:171], v[136:139], v[12:15]
	v_mfma_f32_16x16x32_bf16 v[60:63], v[172:175], v[164:167], v[60:63]
	v_mfma_f32_16x16x32_bf16 v[56:59], v[180:183], v[164:167], v[56:59]
	v_mfma_f32_16x16x32_bf16 v[40:43], v[180:183], v[160:163], v[40:43]
	v_mfma_f32_16x16x32_bf16 v[44:47], v[172:175], v[160:163], v[44:47]
	v_mfma_f32_16x16x32_bf16 v[28:31], v[172:175], v[156:159], v[28:31]
	v_mfma_f32_16x16x32_bf16 v[24:27], v[180:183], v[156:159], v[24:27]
	v_mfma_f32_16x16x32_bf16 v[8:11], v[180:183], v[152:155], v[8:11]
	v_mfma_f32_16x16x32_bf16 v[12:15], v[172:175], v[152:155], v[12:15]
	s_setprio 0
.LBB0_264:
	s_barrier
	v_cndmask_b32_e64 v241, v219, 0, s[52:53]
	v_cndmask_b32_e64 v240, v218, v2, s[52:53]
	v_lshl_add_u64 v[240:241], s[14:15], 0, v[240:241]
	s_mov_b32 m0, s45
	v_add_u32_e32 v168, 0x18000, v232
	v_add_u32_e32 v180, 0x1c000, v232
	v_lshl_add_u64 v[242:243], v[240:241], 0, v[4:5]
	s_waitcnt lgkmcnt(0)
	ds_read_b128 v[148:151], v207 offset:32768
	ds_read_b128 v[164:167], v207 offset:33792
	ds_read_b128 v[144:147], v207 offset:34816
	ds_read_b128 v[160:163], v207 offset:35840
	ds_read_b128 v[140:143], v207 offset:36864
	ds_read_b128 v[156:159], v207 offset:37888
	ds_read_b128 v[136:139], v207 offset:38912
	ds_read_b128 v[152:155], v207 offset:39936
	ds_read_b128 v[184:187], v168
	ds_read_b128 v[188:191], v168 offset:1024
	ds_read_b128 v[192:195], v168 offset:2048
	ds_read_b128 v[196:199], v168 offset:3072
	ds_read_b128 v[168:171], v180
	ds_read_b128 v[172:175], v180 offset:1024
	ds_read_b128 v[176:179], v180 offset:2048
	ds_read_b128 v[180:183], v180 offset:3072
	global_load_lds_dwordx4 v[242:243], off
	v_lshl_add_u64 v[240:241], v[240:241], 0, v[210:211]
	s_mov_b32 m0, s47
	s_nop 0
	global_load_lds_dwordx4 v[240:241], off
	s_waitcnt vmcnt(8)
	s_waitcnt lgkmcnt(0)
	s_barrier
	s_setprio 1
	s_waitcnt lgkmcnt(0)
	v_mfma_f32_16x16x32_bf16 v[132:135], v[184:187], v[148:151], v[132:135]
	v_mfma_f32_16x16x32_bf16 v[128:131], v[192:195], v[148:151], v[128:131]
	v_mfma_f32_16x16x32_bf16 v[112:115], v[192:195], v[144:147], v[112:115]
	v_mfma_f32_16x16x32_bf16 v[116:119], v[184:187], v[144:147], v[116:119]
	v_mfma_f32_16x16x32_bf16 v[100:103], v[184:187], v[140:143], v[100:103]
	v_mfma_f32_16x16x32_bf16 v[96:99], v[192:195], v[140:143], v[96:99]
	v_mfma_f32_16x16x32_bf16 v[80:83], v[192:195], v[136:139], v[80:83]
	v_mfma_f32_16x16x32_bf16 v[84:87], v[184:187], v[136:139], v[84:87]
	v_mfma_f32_16x16x32_bf16 v[132:135], v[188:191], v[164:167], v[132:135]
	v_mfma_f32_16x16x32_bf16 v[128:131], v[196:199], v[164:167], v[128:131]
	v_mfma_f32_16x16x32_bf16 v[112:115], v[196:199], v[160:163], v[112:115]
	v_mfma_f32_16x16x32_bf16 v[116:119], v[188:191], v[160:163], v[116:119]
	v_mfma_f32_16x16x32_bf16 v[100:103], v[188:191], v[156:159], v[100:103]
	v_mfma_f32_16x16x32_bf16 v[96:99], v[196:199], v[156:159], v[96:99]
	v_mfma_f32_16x16x32_bf16 v[80:83], v[196:199], v[152:155], v[80:83]
	v_mfma_f32_16x16x32_bf16 v[84:87], v[188:191], v[152:155], v[84:87]
	s_setprio 0
	s_setprio 1
	v_mfma_f32_16x16x32_bf16 v[124:127], v[168:171], v[148:151], v[124:127]
	v_mfma_f32_16x16x32_bf16 v[120:123], v[176:179], v[148:151], v[120:123]
	v_mfma_f32_16x16x32_bf16 v[104:107], v[176:179], v[144:147], v[104:107]
	v_mfma_f32_16x16x32_bf16 v[108:111], v[168:171], v[144:147], v[108:111]
	v_mfma_f32_16x16x32_bf16 v[92:95], v[168:171], v[140:143], v[92:95]
	v_mfma_f32_16x16x32_bf16 v[88:91], v[176:179], v[140:143], v[88:91]
	v_mfma_f32_16x16x32_bf16 v[72:75], v[176:179], v[136:139], v[72:75]
	v_mfma_f32_16x16x32_bf16 v[76:79], v[168:171], v[136:139], v[76:79]
	v_mfma_f32_16x16x32_bf16 v[124:127], v[172:175], v[164:167], v[124:127]
	v_mfma_f32_16x16x32_bf16 v[120:123], v[180:183], v[164:167], v[120:123]
	v_mfma_f32_16x16x32_bf16 v[104:107], v[180:183], v[160:163], v[104:107]
	v_mfma_f32_16x16x32_bf16 v[108:111], v[172:175], v[160:163], v[108:111]
	v_mfma_f32_16x16x32_bf16 v[92:95], v[172:175], v[156:159], v[92:95]
	v_mfma_f32_16x16x32_bf16 v[88:91], v[180:183], v[156:159], v[88:91]
	v_mfma_f32_16x16x32_bf16 v[72:75], v[180:183], v[152:155], v[72:75]
	v_mfma_f32_16x16x32_bf16 v[76:79], v[172:175], v[152:155], v[76:79]
	s_setprio 0
	s_barrier
	s_and_b64 vcc, exec, s[50:51]
	s_cbranch_vccnz .LBB0_266
	ds_read_b128 v[148:151], v207 offset:49152
	ds_read_b128 v[164:167], v207 offset:50176
	ds_read_b128 v[144:147], v207 offset:51200
	ds_read_b128 v[160:163], v207 offset:52224
	ds_read_b128 v[140:143], v207 offset:53248
	ds_read_b128 v[156:159], v207 offset:54272
	ds_read_b128 v[136:139], v207 offset:55296
	ds_read_b128 v[152:155], v207 offset:56320
.LBB0_266:
	s_mov_b32 m0, s64
	v_lshl_add_u64 v[224:225], v[224:225], 0, s[0:1]
	s_add_u32 s12, s12, 0x80080
	global_load_lds_dwordx4 v[224:225], off
	v_lshl_add_u64 v[224:225], v[226:227], 0, s[0:1]
	s_mov_b32 m0, s65
	s_addc_u32 s13, s13, 0
	global_load_lds_dwordx4 v[224:225], off
	v_lshl_add_u64 v[224:225], s[12:13], 0, v[208:209]
	s_mov_b32 m0, s68
	s_and_b64 vcc, exec, s[50:51]
	global_load_lds_dwordx4 v[224:225], off
	v_lshl_add_u64 v[224:225], s[12:13], 0, v[212:213]
	s_mov_b32 m0, s69
	s_nop 0
	global_load_lds_dwordx4 v[224:225], off
	v_lshl_add_u64 v[224:225], v[228:229], 0, s[0:1]
	s_mov_b32 m0, s66
	s_nop 0
	global_load_lds_dwordx4 v[224:225], off
	v_lshl_add_u64 v[224:225], v[230:231], 0, s[0:1]
	s_mov_b32 m0, s67
	s_nop 0
	global_load_lds_dwordx4 v[224:225], off
	s_waitcnt vmcnt(8)
	s_waitcnt lgkmcnt(0)
	s_barrier
	s_cbranch_vccnz .LBB0_259
	s_setprio 1
	s_waitcnt lgkmcnt(0)
	v_mfma_f32_16x16x32_bf16 v[68:71], v[184:187], v[148:151], v[68:71]
	v_mfma_f32_16x16x32_bf16 v[64:67], v[192:195], v[148:151], v[64:67]
	v_mfma_f32_16x16x32_bf16 v[48:51], v[192:195], v[144:147], v[48:51]
	v_mfma_f32_16x16x32_bf16 v[52:55], v[184:187], v[144:147], v[52:55]
	v_mfma_f32_16x16x32_bf16 v[36:39], v[184:187], v[140:143], v[36:39]
	v_mfma_f32_16x16x32_bf16 v[32:35], v[192:195], v[140:143], v[32:35]
	v_mfma_f32_16x16x32_bf16 v[16:19], v[192:195], v[136:139], v[16:19]
	v_mfma_f32_16x16x32_bf16 v[20:23], v[184:187], v[136:139], v[20:23]
	v_mfma_f32_16x16x32_bf16 v[68:71], v[188:191], v[164:167], v[68:71]
	v_mfma_f32_16x16x32_bf16 v[64:67], v[196:199], v[164:167], v[64:67]
	v_mfma_f32_16x16x32_bf16 v[48:51], v[196:199], v[160:163], v[48:51]
	v_mfma_f32_16x16x32_bf16 v[52:55], v[188:191], v[160:163], v[52:55]
	v_mfma_f32_16x16x32_bf16 v[36:39], v[188:191], v[156:159], v[36:39]
	v_mfma_f32_16x16x32_bf16 v[32:35], v[196:199], v[156:159], v[32:35]
	v_mfma_f32_16x16x32_bf16 v[16:19], v[196:199], v[152:155], v[16:19]
	v_mfma_f32_16x16x32_bf16 v[20:23], v[188:191], v[152:155], v[20:23]
	s_setprio 0
	s_setprio 1
	v_mfma_f32_16x16x32_bf16 v[60:63], v[168:171], v[148:151], v[60:63]
	v_mfma_f32_16x16x32_bf16 v[56:59], v[176:179], v[148:151], v[56:59]
	v_mfma_f32_16x16x32_bf16 v[40:43], v[176:179], v[144:147], v[40:43]
	v_mfma_f32_16x16x32_bf16 v[44:47], v[168:171], v[144:147], v[44:47]
	v_mfma_f32_16x16x32_bf16 v[28:31], v[168:171], v[140:143], v[28:31]
	v_mfma_f32_16x16x32_bf16 v[24:27], v[176:179], v[140:143], v[24:27]
	v_mfma_f32_16x16x32_bf16 v[8:11], v[176:179], v[136:139], v[8:11]
	v_mfma_f32_16x16x32_bf16 v[12:15], v[168:171], v[136:139], v[12:15]
	v_mfma_f32_16x16x32_bf16 v[60:63], v[172:175], v[164:167], v[60:63]
	v_mfma_f32_16x16x32_bf16 v[56:59], v[180:183], v[164:167], v[56:59]
	v_mfma_f32_16x16x32_bf16 v[40:43], v[180:183], v[160:163], v[40:43]
	v_mfma_f32_16x16x32_bf16 v[44:47], v[172:175], v[160:163], v[44:47]
	v_mfma_f32_16x16x32_bf16 v[28:31], v[172:175], v[156:159], v[28:31]
	v_mfma_f32_16x16x32_bf16 v[24:27], v[180:183], v[156:159], v[24:27]
	v_mfma_f32_16x16x32_bf16 v[8:11], v[180:183], v[152:155], v[8:11]
	v_mfma_f32_16x16x32_bf16 v[12:15], v[172:175], v[152:155], v[12:15]
	s_setprio 0
	s_branch .LBB0_259

.LBB0_369:
	v_add_u32_e32 v168, 0x10000, v232
	v_add_u32_e32 v180, 0x14000, v232
	v_lshl_add_u64 v[224:225], v[222:223], 0, s[60:61]
	s_add_i32 m0, s9, 0xc000
	s_waitcnt lgkmcnt(0)
	ds_read_b128 v[148:151], v207
	ds_read_b128 v[164:167], v207 offset:1024
	ds_read_b128 v[144:147], v207 offset:2048
	ds_read_b128 v[160:163], v207 offset:3072
	ds_read_b128 v[140:143], v207 offset:4096
	ds_read_b128 v[156:159], v207 offset:5120
	ds_read_b128 v[136:139], v207 offset:6144
	ds_read_b128 v[152:155], v207 offset:7168
	ds_read_b128 v[184:187], v168
	ds_read_b128 v[188:191], v168 offset:1024
	ds_read_b128 v[192:195], v168 offset:2048
	ds_read_b128 v[196:199], v168 offset:3072
	ds_read_b128 v[168:171], v180
	ds_read_b128 v[172:175], v180 offset:1024
	ds_read_b128 v[176:179], v180 offset:2048
	ds_read_b128 v[180:183], v180 offset:3072
	global_load_lds_dwordx4 v[224:225], off
	v_lshl_add_u64 v[224:225], v[220:221], 0, s[60:61]
	s_add_i32 m0, s9, 0xe000
	s_nop 0
	global_load_lds_dwordx4 v[224:225], off
	s_waitcnt vmcnt(8)
	s_waitcnt lgkmcnt(0)
	s_barrier
	s_setprio 1
	s_waitcnt lgkmcnt(0)
	v_mfma_f32_16x16x32_bf16 v[132:135], v[184:187], v[148:151], v[132:135]
	v_mfma_f32_16x16x32_bf16 v[128:131], v[192:195], v[148:151], v[128:131]
	v_mfma_f32_16x16x32_bf16 v[120:123], v[192:195], v[144:147], v[120:123]
	v_mfma_f32_16x16x32_bf16 v[124:127], v[184:187], v[144:147], v[124:127]
	v_mfma_f32_16x16x32_bf16 v[108:111], v[184:187], v[140:143], v[108:111]
	v_mfma_f32_16x16x32_bf16 v[104:107], v[192:195], v[140:143], v[104:107]
	v_mfma_f32_16x16x32_bf16 v[88:91], v[192:195], v[136:139], v[88:91]
	v_mfma_f32_16x16x32_bf16 v[92:95], v[184:187], v[136:139], v[92:95]
	v_mfma_f32_16x16x32_bf16 v[132:135], v[188:191], v[164:167], v[132:135]
	v_mfma_f32_16x16x32_bf16 v[128:131], v[196:199], v[164:167], v[128:131]
	v_mfma_f32_16x16x32_bf16 v[120:123], v[196:199], v[160:163], v[120:123]
	v_mfma_f32_16x16x32_bf16 v[124:127], v[188:191], v[160:163], v[124:127]
	v_mfma_f32_16x16x32_bf16 v[108:111], v[188:191], v[156:159], v[108:111]
	v_mfma_f32_16x16x32_bf16 v[104:107], v[196:199], v[156:159], v[104:107]
	v_mfma_f32_16x16x32_bf16 v[88:91], v[196:199], v[152:155], v[88:91]
	v_mfma_f32_16x16x32_bf16 v[92:95], v[188:191], v[152:155], v[92:95]
	s_setprio 0
	s_setprio 1
	v_mfma_f32_16x16x32_bf16 v[116:119], v[168:171], v[148:151], v[116:119]
	v_mfma_f32_16x16x32_bf16 v[112:115], v[176:179], v[148:151], v[112:115]
	v_mfma_f32_16x16x32_bf16 v[96:99], v[176:179], v[144:147], v[96:99]
	v_mfma_f32_16x16x32_bf16 v[100:103], v[168:171], v[144:147], v[100:103]
	v_mfma_f32_16x16x32_bf16 v[84:87], v[168:171], v[140:143], v[84:87]
	v_mfma_f32_16x16x32_bf16 v[80:83], v[176:179], v[140:143], v[80:83]
	v_mfma_f32_16x16x32_bf16 v[72:75], v[176:179], v[136:139], v[72:75]
	v_mfma_f32_16x16x32_bf16 v[76:79], v[168:171], v[136:139], v[76:79]
	v_mfma_f32_16x16x32_bf16 v[116:119], v[172:175], v[164:167], v[116:119]
	v_mfma_f32_16x16x32_bf16 v[112:115], v[180:183], v[164:167], v[112:115]
	v_mfma_f32_16x16x32_bf16 v[96:99], v[180:183], v[160:163], v[96:99]
	v_mfma_f32_16x16x32_bf16 v[100:103], v[172:175], v[160:163], v[100:103]
	v_mfma_f32_16x16x32_bf16 v[84:87], v[172:175], v[156:159], v[84:87]
	v_mfma_f32_16x16x32_bf16 v[80:83], v[180:183], v[156:159], v[80:83]
	v_mfma_f32_16x16x32_bf16 v[72:75], v[180:183], v[152:155], v[72:75]
	v_mfma_f32_16x16x32_bf16 v[76:79], v[172:175], v[152:155], v[76:79]
	s_setprio 0
	s_barrier
	v_cndmask_b32_e64 v204, 0, 1, s[58:59]
	v_cmp_ne_u32_e64 s[50:51], 1, v204
	s_andn2_b64 vcc, exec, s[58:59]
	s_cbranch_vccnz .LBB0_371
	ds_read_b128 v[148:151], v207 offset:16384
	ds_read_b128 v[164:167], v207 offset:17408
	ds_read_b128 v[144:147], v207 offset:18432
	ds_read_b128 v[160:163], v207 offset:19456
	ds_read_b128 v[140:143], v207 offset:20480
	ds_read_b128 v[156:159], v207 offset:21504
	ds_read_b128 v[136:139], v207 offset:22528
	ds_read_b128 v[152:155], v207 offset:23552
.LBB0_371:
	s_add_u32 s12, s24, s60
	s_addc_u32 s13, s25, s61
	s_add_u32 s14, s12, 0x100
	s_addc_u32 s15, s13, 0
	s_add_u32 s73, s26, s60
	s_addc_u32 s74, s27, s61
	s_cmpk_eq_i32 s60, 0xf00
	s_cselect_b64 s[52:53], -1, 0
	s_and_b64 s[12:13], s[52:53], exec
	s_cselect_b32 s13, s37, s74
	s_cselect_b32 s12, s43, s73
	s_mov_b32 m0, s38
	s_cselect_b32 s15, s7, s15
	s_cselect_b32 s14, s33, s14
	v_lshl_add_u64 v[224:225], s[12:13], 0, v[208:209]
	s_add_u32 s74, s12, 0x80000
	global_load_lds_dwordx4 v[224:225], off
	v_lshl_add_u64 v[226:227], s[12:13], 0, v[212:213]
	s_mov_b32 m0, s39
	s_addc_u32 s75, s13, 0
	global_load_lds_dwordx4 v[226:227], off
	v_lshl_add_u64 v[228:229], s[74:75], 0, v[208:209]
	s_mov_b32 m0, s40
	v_lshl_add_u64 v[230:231], s[14:15], 0, v[210:211]
	global_load_lds_dwordx4 v[228:229], off
	v_lshl_add_u64 v[228:229], s[74:75], 0, v[212:213]
	s_mov_b32 m0, s41
	s_and_b64 vcc, exec, s[50:51]
	global_load_lds_dwordx4 v[228:229], off
	v_lshl_add_u64 v[228:229], s[14:15], 0, v[4:5]
	s_mov_b32 m0, s9
	s_nop 0
	global_load_lds_dwordx4 v[228:229], off
	s_mov_b32 m0, s47
	s_nop 0
	global_load_lds_dwordx4 v[230:231], off
	s_waitcnt vmcnt(8)
	s_waitcnt lgkmcnt(0)
	s_barrier
	s_cbranch_vccnz .LBB0_373
	s_setprio 1
	s_waitcnt lgkmcnt(0)
	v_mfma_f32_16x16x32_bf16 v[68:71], v[184:187], v[148:151], v[68:71]
	v_mfma_f32_16x16x32_bf16 v[64:67], v[192:195], v[148:151], v[64:67]
	v_mfma_f32_16x16x32_bf16 v[48:51], v[192:195], v[144:147], v[48:51]
	v_mfma_f32_16x16x32_bf16 v[52:55], v[184:187], v[144:147], v[52:55]
	v_mfma_f32_16x16x32_bf16 v[36:39], v[184:187], v[140:143], v[36:39]
	v_mfma_f32_16x16x32_bf16 v[32:35], v[192:195], v[140:143], v[32:35]
	v_mfma_f32_16x16x32_bf16 v[16:19], v[192:195], v[136:139], v[16:19]
	v_mfma_f32_16x16x32_bf16 v[20:23], v[184:187], v[136:139], v[20:23]
	v_mfma_f32_16x16x32_bf16 v[68:71], v[188:191], v[164:167], v[68:71]
	v_mfma_f32_16x16x32_bf16 v[64:67], v[196:199], v[164:167], v[64:67]
	v_mfma_f32_16x16x32_bf16 v[48:51], v[196:199], v[160:163], v[48:51]
	v_mfma_f32_16x16x32_bf16 v[52:55], v[188:191], v[160:163], v[52:55]
	v_mfma_f32_16x16x32_bf16 v[36:39], v[188:191], v[156:159], v[36:39]
	v_mfma_f32_16x16x32_bf16 v[32:35], v[196:199], v[156:159], v[32:35]
	v_mfma_f32_16x16x32_bf16 v[16:19], v[196:199], v[152:155], v[16:19]
	v_mfma_f32_16x16x32_bf16 v[20:23], v[188:191], v[152:155], v[20:23]
	s_setprio 0
	s_setprio 1
	v_mfma_f32_16x16x32_bf16 v[60:63], v[168:171], v[148:151], v[60:63]
	v_mfma_f32_16x16x32_bf16 v[56:59], v[176:179], v[148:151], v[56:59]
	v_mfma_f32_16x16x32_bf16 v[40:43], v[176:179], v[144:147], v[40:43]
	v_mfma_f32_16x16x32_bf16 v[44:47], v[168:171], v[144:147], v[44:47]
	v_mfma_f32_16x16x32_bf16 v[28:31], v[168:171], v[140:143], v[28:31]
	v_mfma_f32_16x16x32_bf16 v[24:27], v[176:179], v[140:143], v[24:27]
	v_mfma_f32_16x16x32_bf16 v[8:11], v[176:179], v[136:139], v[8:11]
	v_mfma_f32_16x16x32_bf16 v[12:15], v[168:171], v[136:139], v[12:15]
	v_mfma_f32_16x16x32_bf16 v[60:63], v[172:175], v[164:167], v[60:63]
	v_mfma_f32_16x16x32_bf16 v[56:59], v[180:183], v[164:167], v[56:59]
	v_mfma_f32_16x16x32_bf16 v[40:43], v[180:183], v[160:163], v[40:43]
	v_mfma_f32_16x16x32_bf16 v[44:47], v[172:175], v[160:163], v[44:47]
	v_mfma_f32_16x16x32_bf16 v[28:31], v[172:175], v[156:159], v[28:31]
	v_mfma_f32_16x16x32_bf16 v[24:27], v[180:183], v[156:159], v[24:27]
	v_mfma_f32_16x16x32_bf16 v[8:11], v[180:183], v[152:155], v[8:11]
	v_mfma_f32_16x16x32_bf16 v[12:15], v[172:175], v[152:155], v[12:15]
	s_setprio 0
.LBB0_373:
	s_barrier
	v_cndmask_b32_e64 v241, v219, 0, s[52:53]
	v_cndmask_b32_e64 v240, v218, v2, s[52:53]
	v_lshl_add_u64 v[240:241], s[14:15], 0, v[240:241]
	s_mov_b32 m0, s62
	v_add_u32_e32 v168, 0x18000, v232
	v_add_u32_e32 v180, 0x1c000, v232
	v_lshl_add_u64 v[242:243], v[240:241], 0, v[4:5]
	s_waitcnt lgkmcnt(0)
	ds_read_b128 v[148:151], v207 offset:32768
	ds_read_b128 v[164:167], v207 offset:33792
	ds_read_b128 v[144:147], v207 offset:34816
	ds_read_b128 v[160:163], v207 offset:35840
	ds_read_b128 v[140:143], v207 offset:36864
	ds_read_b128 v[156:159], v207 offset:37888
	ds_read_b128 v[136:139], v207 offset:38912
	ds_read_b128 v[152:155], v207 offset:39936
	ds_read_b128 v[184:187], v168
	ds_read_b128 v[188:191], v168 offset:1024
	ds_read_b128 v[192:195], v168 offset:2048
	ds_read_b128 v[196:199], v168 offset:3072
	ds_read_b128 v[168:171], v180
	ds_read_b128 v[172:175], v180 offset:1024
	ds_read_b128 v[176:179], v180 offset:2048
	ds_read_b128 v[180:183], v180 offset:3072
	global_load_lds_dwordx4 v[242:243], off
	v_lshl_add_u64 v[240:241], v[240:241], 0, v[210:211]
	s_mov_b32 m0, s63
	s_nop 0
	global_load_lds_dwordx4 v[240:241], off
	s_waitcnt vmcnt(8)
	s_waitcnt lgkmcnt(0)
	s_barrier
	s_setprio 1
	s_waitcnt lgkmcnt(0)
	v_mfma_f32_16x16x32_bf16 v[132:135], v[184:187], v[148:151], v[132:135]
	v_mfma_f32_16x16x32_bf16 v[128:131], v[192:195], v[148:151], v[128:131]
	v_mfma_f32_16x16x32_bf16 v[120:123], v[192:195], v[144:147], v[120:123]
	v_mfma_f32_16x16x32_bf16 v[124:127], v[184:187], v[144:147], v[124:127]
	v_mfma_f32_16x16x32_bf16 v[108:111], v[184:187], v[140:143], v[108:111]
	v_mfma_f32_16x16x32_bf16 v[104:107], v[192:195], v[140:143], v[104:107]
	v_mfma_f32_16x16x32_bf16 v[88:91], v[192:195], v[136:139], v[88:91]
	v_mfma_f32_16x16x32_bf16 v[92:95], v[184:187], v[136:139], v[92:95]
	v_mfma_f32_16x16x32_bf16 v[132:135], v[188:191], v[164:167], v[132:135]
	v_mfma_f32_16x16x32_bf16 v[128:131], v[196:199], v[164:167], v[128:131]
	v_mfma_f32_16x16x32_bf16 v[120:123], v[196:199], v[160:163], v[120:123]
	v_mfma_f32_16x16x32_bf16 v[124:127], v[188:191], v[160:163], v[124:127]
	v_mfma_f32_16x16x32_bf16 v[108:111], v[188:191], v[156:159], v[108:111]
	v_mfma_f32_16x16x32_bf16 v[104:107], v[196:199], v[156:159], v[104:107]
	v_mfma_f32_16x16x32_bf16 v[88:91], v[196:199], v[152:155], v[88:91]
	v_mfma_f32_16x16x32_bf16 v[92:95], v[188:191], v[152:155], v[92:95]
	s_setprio 0
	s_setprio 1
	v_mfma_f32_16x16x32_bf16 v[116:119], v[168:171], v[148:151], v[116:119]
	v_mfma_f32_16x16x32_bf16 v[112:115], v[176:179], v[148:151], v[112:115]
	v_mfma_f32_16x16x32_bf16 v[96:99], v[176:179], v[144:147], v[96:99]
	v_mfma_f32_16x16x32_bf16 v[100:103], v[168:171], v[144:147], v[100:103]
	v_mfma_f32_16x16x32_bf16 v[84:87], v[168:171], v[140:143], v[84:87]
	v_mfma_f32_16x16x32_bf16 v[80:83], v[176:179], v[140:143], v[80:83]
	v_mfma_f32_16x16x32_bf16 v[72:75], v[176:179], v[136:139], v[72:75]
	v_mfma_f32_16x16x32_bf16 v[76:79], v[168:171], v[136:139], v[76:79]
	v_mfma_f32_16x16x32_bf16 v[116:119], v[172:175], v[164:167], v[116:119]
	v_mfma_f32_16x16x32_bf16 v[112:115], v[180:183], v[164:167], v[112:115]
	v_mfma_f32_16x16x32_bf16 v[96:99], v[180:183], v[160:163], v[96:99]
	v_mfma_f32_16x16x32_bf16 v[100:103], v[172:175], v[160:163], v[100:103]
	v_mfma_f32_16x16x32_bf16 v[84:87], v[172:175], v[156:159], v[84:87]
	v_mfma_f32_16x16x32_bf16 v[80:83], v[180:183], v[156:159], v[80:83]
	v_mfma_f32_16x16x32_bf16 v[72:75], v[180:183], v[152:155], v[72:75]
	v_mfma_f32_16x16x32_bf16 v[76:79], v[172:175], v[152:155], v[76:79]
	s_setprio 0
	s_barrier
	s_and_b64 vcc, exec, s[50:51]
	s_cbranch_vccnz .LBB0_375
	ds_read_b128 v[148:151], v207 offset:49152
	ds_read_b128 v[164:167], v207 offset:50176
	ds_read_b128 v[144:147], v207 offset:51200
	ds_read_b128 v[160:163], v207 offset:52224
	ds_read_b128 v[140:143], v207 offset:53248
	ds_read_b128 v[156:159], v207 offset:54272
	ds_read_b128 v[136:139], v207 offset:55296
	ds_read_b128 v[152:155], v207 offset:56320

.LBB0_559:
	v_add_u32_e32 v168, 0x10000, v240
	v_add_u32_e32 v180, 0x14000, v240
	v_lshl_add_u64 v[226:227], v[224:225], 0, s[64:65]
	s_add_i32 m0, s38, 0xc000
	s_waitcnt lgkmcnt(0)
	ds_read_b128 v[148:151], v239
	ds_read_b128 v[164:167], v239 offset:1024
	ds_read_b128 v[144:147], v239 offset:2048
	ds_read_b128 v[160:163], v239 offset:3072
	ds_read_b128 v[140:143], v239 offset:4096
	ds_read_b128 v[156:159], v239 offset:5120
	ds_read_b128 v[136:139], v239 offset:6144
	ds_read_b128 v[152:155], v239 offset:7168
	ds_read_b128 v[184:187], v168
	ds_read_b128 v[188:191], v168 offset:1024
	ds_read_b128 v[192:195], v168 offset:2048
	ds_read_b128 v[196:199], v168 offset:3072
	ds_read_b128 v[168:171], v180
	ds_read_b128 v[172:175], v180 offset:1024
	ds_read_b128 v[176:179], v180 offset:2048
	ds_read_b128 v[180:183], v180 offset:3072
	global_load_lds_dwordx4 v[226:227], off
	v_lshl_add_u64 v[226:227], v[222:223], 0, s[64:65]
	s_add_i32 m0, s38, 0xe000
	s_nop 0
	global_load_lds_dwordx4 v[226:227], off
	s_waitcnt vmcnt(8)
	s_waitcnt lgkmcnt(0)
	s_barrier
	s_setprio 1
	s_waitcnt lgkmcnt(0)
	v_mfma_f32_16x16x32_bf16 v[132:135], v[184:187], v[148:151], v[132:135]
	v_mfma_f32_16x16x32_bf16 v[128:131], v[192:195], v[148:151], v[128:131]
	v_mfma_f32_16x16x32_bf16 v[112:115], v[192:195], v[144:147], v[112:115]
	v_mfma_f32_16x16x32_bf16 v[116:119], v[184:187], v[144:147], v[116:119]
	v_mfma_f32_16x16x32_bf16 v[100:103], v[184:187], v[140:143], v[100:103]
	v_mfma_f32_16x16x32_bf16 v[96:99], v[192:195], v[140:143], v[96:99]
	v_mfma_f32_16x16x32_bf16 v[80:83], v[192:195], v[136:139], v[80:83]
	v_mfma_f32_16x16x32_bf16 v[84:87], v[184:187], v[136:139], v[84:87]
	v_mfma_f32_16x16x32_bf16 v[132:135], v[188:191], v[164:167], v[132:135]
	v_mfma_f32_16x16x32_bf16 v[128:131], v[196:199], v[164:167], v[128:131]
	v_mfma_f32_16x16x32_bf16 v[112:115], v[196:199], v[160:163], v[112:115]
	v_mfma_f32_16x16x32_bf16 v[116:119], v[188:191], v[160:163], v[116:119]
	v_mfma_f32_16x16x32_bf16 v[100:103], v[188:191], v[156:159], v[100:103]
	v_mfma_f32_16x16x32_bf16 v[96:99], v[196:199], v[156:159], v[96:99]
	v_mfma_f32_16x16x32_bf16 v[80:83], v[196:199], v[152:155], v[80:83]
	v_mfma_f32_16x16x32_bf16 v[84:87], v[188:191], v[152:155], v[84:87]
	s_setprio 0
	s_setprio 1
	v_mfma_f32_16x16x32_bf16 v[124:127], v[168:171], v[148:151], v[124:127]
	v_mfma_f32_16x16x32_bf16 v[120:123], v[176:179], v[148:151], v[120:123]
	v_mfma_f32_16x16x32_bf16 v[104:107], v[176:179], v[144:147], v[104:107]
	v_mfma_f32_16x16x32_bf16 v[108:111], v[168:171], v[144:147], v[108:111]
	v_mfma_f32_16x16x32_bf16 v[92:95], v[168:171], v[140:143], v[92:95]
	v_mfma_f32_16x16x32_bf16 v[88:91], v[176:179], v[140:143], v[88:91]
	v_mfma_f32_16x16x32_bf16 v[72:75], v[176:179], v[136:139], v[72:75]
	v_mfma_f32_16x16x32_bf16 v[76:79], v[168:171], v[136:139], v[76:79]
	v_mfma_f32_16x16x32_bf16 v[124:127], v[172:175], v[164:167], v[124:127]
	v_mfma_f32_16x16x32_bf16 v[120:123], v[180:183], v[164:167], v[120:123]
	v_mfma_f32_16x16x32_bf16 v[104:107], v[180:183], v[160:163], v[104:107]
	v_mfma_f32_16x16x32_bf16 v[108:111], v[172:175], v[160:163], v[108:111]
	v_mfma_f32_16x16x32_bf16 v[92:95], v[172:175], v[156:159], v[92:95]
	v_mfma_f32_16x16x32_bf16 v[88:91], v[180:183], v[156:159], v[88:91]
	v_mfma_f32_16x16x32_bf16 v[72:75], v[180:183], v[152:155], v[72:75]
	v_mfma_f32_16x16x32_bf16 v[76:79], v[172:175], v[152:155], v[76:79]
	s_setprio 0
	s_barrier
	v_cndmask_b32_e64 v204, 0, 1, s[62:63]
	v_cmp_ne_u32_e64 s[50:51], 1, v204
	s_andn2_b64 vcc, exec, s[62:63]
	s_cbranch_vccnz .LBB0_561
	ds_read_b128 v[148:151], v239 offset:16384
	ds_read_b128 v[164:167], v239 offset:17408
	ds_read_b128 v[144:147], v239 offset:18432
	ds_read_b128 v[160:163], v239 offset:19456
	ds_read_b128 v[140:143], v239 offset:20480
	ds_read_b128 v[156:159], v239 offset:21504
	ds_read_b128 v[136:139], v239 offset:22528
	ds_read_b128 v[152:155], v239 offset:23552
.LBB0_561:
	s_add_u32 s12, s60, s64
	s_addc_u32 s13, s61, s65
	s_add_u32 s14, s12, 0x100
	s_addc_u32 s15, s13, 0
	s_add_u32 s79, s26, s64
	s_addc_u32 s80, s27, s65
	s_cmpk_eq_i32 s64, 0x300
	s_cselect_b64 s[52:53], -1, 0
	s_and_b64 s[12:13], s[52:53], exec
	s_cselect_b32 s13, s17, s80
	s_cselect_b32 s12, s35, s79
	s_mov_b32 m0, s39
	s_cselect_b32 s15, s21, s15
	s_cselect_b32 s14, s33, s14
	v_lshl_add_u64 v[226:227], s[12:13], 0, v[4:5]
	s_add_u32 s80, s12, 0x20000
	global_load_lds_dwordx4 v[226:227], off
	v_lshl_add_u64 v[228:229], s[12:13], 0, v[208:209]
	s_mov_b32 m0, s40
	s_addc_u32 s81, s13, 0
	global_load_lds_dwordx4 v[228:229], off
	v_lshl_add_u64 v[230:231], s[80:81], 0, v[4:5]
	s_mov_b32 m0, s41
	v_lshl_add_u64 v[232:233], s[14:15], 0, v[208:209]
	global_load_lds_dwordx4 v[230:231], off
	v_lshl_add_u64 v[230:231], s[80:81], 0, v[208:209]
	s_mov_b32 m0, s47
	s_and_b64 vcc, exec, s[50:51]
	global_load_lds_dwordx4 v[230:231], off
	v_lshl_add_u64 v[230:231], s[14:15], 0, v[4:5]
	s_mov_b32 m0, s38
	s_nop 0
	global_load_lds_dwordx4 v[230:231], off
	s_mov_b32 m0, s59
	s_nop 0
	global_load_lds_dwordx4 v[232:233], off
	s_waitcnt vmcnt(8)
	s_waitcnt lgkmcnt(0)
	s_barrier
	s_cbranch_vccnz .LBB0_563
	s_setprio 1
	s_waitcnt lgkmcnt(0)
	v_mfma_f32_16x16x32_bf16 v[68:71], v[184:187], v[148:151], v[68:71]
	v_mfma_f32_16x16x32_bf16 v[64:67], v[192:195], v[148:151], v[64:67]
	v_mfma_f32_16x16x32_bf16 v[48:51], v[192:195], v[144:147], v[48:51]
	v_mfma_f32_16x16x32_bf16 v[52:55], v[184:187], v[144:147], v[52:55]
	v_mfma_f32_16x16x32_bf16 v[36:39], v[184:187], v[140:143], v[36:39]
	v_mfma_f32_16x16x32_bf16 v[32:35], v[192:195], v[140:143], v[32:35]
	v_mfma_f32_16x16x32_bf16 v[16:19], v[192:195], v[136:139], v[16:19]
	v_mfma_f32_16x16x32_bf16 v[20:23], v[184:187], v[136:139], v[20:23]
	v_mfma_f32_16x16x32_bf16 v[68:71], v[188:191], v[164:167], v[68:71]
	v_mfma_f32_16x16x32_bf16 v[64:67], v[196:199], v[164:167], v[64:67]
	v_mfma_f32_16x16x32_bf16 v[48:51], v[196:199], v[160:163], v[48:51]
	v_mfma_f32_16x16x32_bf16 v[52:55], v[188:191], v[160:163], v[52:55]
	v_mfma_f32_16x16x32_bf16 v[36:39], v[188:191], v[156:159], v[36:39]
	v_mfma_f32_16x16x32_bf16 v[32:35], v[196:199], v[156:159], v[32:35]
	v_mfma_f32_16x16x32_bf16 v[16:19], v[196:199], v[152:155], v[16:19]
	v_mfma_f32_16x16x32_bf16 v[20:23], v[188:191], v[152:155], v[20:23]
	s_setprio 0
	s_setprio 1
	v_mfma_f32_16x16x32_bf16 v[60:63], v[168:171], v[148:151], v[60:63]
	v_mfma_f32_16x16x32_bf16 v[56:59], v[176:179], v[148:151], v[56:59]
	v_mfma_f32_16x16x32_bf16 v[40:43], v[176:179], v[144:147], v[40:43]
	v_mfma_f32_16x16x32_bf16 v[44:47], v[168:171], v[144:147], v[44:47]
	v_mfma_f32_16x16x32_bf16 v[28:31], v[168:171], v[140:143], v[28:31]
	v_mfma_f32_16x16x32_bf16 v[24:27], v[176:179], v[140:143], v[24:27]
	v_mfma_f32_16x16x32_bf16 v[8:11], v[176:179], v[136:139], v[8:11]
	v_mfma_f32_16x16x32_bf16 v[12:15], v[168:171], v[136:139], v[12:15]
	v_mfma_f32_16x16x32_bf16 v[60:63], v[172:175], v[164:167], v[60:63]
	v_mfma_f32_16x16x32_bf16 v[56:59], v[180:183], v[164:167], v[56:59]
	v_mfma_f32_16x16x32_bf16 v[40:43], v[180:183], v[160:163], v[40:43]
	v_mfma_f32_16x16x32_bf16 v[44:47], v[172:175], v[160:163], v[44:47]
	v_mfma_f32_16x16x32_bf16 v[28:31], v[172:175], v[156:159], v[28:31]
	v_mfma_f32_16x16x32_bf16 v[24:27], v[180:183], v[156:159], v[24:27]
	v_mfma_f32_16x16x32_bf16 v[8:11], v[180:183], v[152:155], v[8:11]
	v_mfma_f32_16x16x32_bf16 v[12:15], v[172:175], v[152:155], v[12:15]
	s_setprio 0
.LBB0_563:
	s_barrier
	v_cndmask_b32_e64 v243, v221, 0, s[52:53]
	v_cndmask_b32_e64 v242, v220, v2, s[52:53]
	v_lshl_add_u64 v[242:243], s[14:15], 0, v[242:243]
	s_mov_b32 m0, s66
	v_add_u32_e32 v168, 0x18000, v240
	v_add_u32_e32 v180, 0x1c000, v240
	v_lshl_add_u64 v[204:205], v[242:243], 0, v[4:5]
	s_waitcnt lgkmcnt(0)
	ds_read_b128 v[148:151], v239 offset:32768
	ds_read_b128 v[164:167], v239 offset:33792
	ds_read_b128 v[144:147], v239 offset:34816
	ds_read_b128 v[160:163], v239 offset:35840
	ds_read_b128 v[140:143], v239 offset:36864
	ds_read_b128 v[156:159], v239 offset:37888
	ds_read_b128 v[136:139], v239 offset:38912
	ds_read_b128 v[152:155], v239 offset:39936
	ds_read_b128 v[184:187], v168
	ds_read_b128 v[188:191], v168 offset:1024
	ds_read_b128 v[192:195], v168 offset:2048
	ds_read_b128 v[196:199], v168 offset:3072
	ds_read_b128 v[168:171], v180
	ds_read_b128 v[172:175], v180 offset:1024
	ds_read_b128 v[176:179], v180 offset:2048
	ds_read_b128 v[180:183], v180 offset:3072
	global_load_lds_dwordx4 v[204:205], off
	v_lshl_add_u64 v[204:205], v[242:243], 0, v[208:209]
	s_mov_b32 m0, s67
	s_nop 0
	global_load_lds_dwordx4 v[204:205], off
	s_waitcnt vmcnt(8)
	s_waitcnt lgkmcnt(0)
	s_barrier
	s_setprio 1
	s_waitcnt lgkmcnt(0)
	v_mfma_f32_16x16x32_bf16 v[132:135], v[184:187], v[148:151], v[132:135]
	v_mfma_f32_16x16x32_bf16 v[128:131], v[192:195], v[148:151], v[128:131]
	v_mfma_f32_16x16x32_bf16 v[112:115], v[192:195], v[144:147], v[112:115]
	v_mfma_f32_16x16x32_bf16 v[116:119], v[184:187], v[144:147], v[116:119]
	v_mfma_f32_16x16x32_bf16 v[100:103], v[184:187], v[140:143], v[100:103]
	v_mfma_f32_16x16x32_bf16 v[96:99], v[192:195], v[140:143], v[96:99]
	v_mfma_f32_16x16x32_bf16 v[80:83], v[192:195], v[136:139], v[80:83]
	v_mfma_f32_16x16x32_bf16 v[84:87], v[184:187], v[136:139], v[84:87]
	v_mfma_f32_16x16x32_bf16 v[132:135], v[188:191], v[164:167], v[132:135]
	v_mfma_f32_16x16x32_bf16 v[128:131], v[196:199], v[164:167], v[128:131]
	v_mfma_f32_16x16x32_bf16 v[112:115], v[196:199], v[160:163], v[112:115]
	v_mfma_f32_16x16x32_bf16 v[116:119], v[188:191], v[160:163], v[116:119]
	v_mfma_f32_16x16x32_bf16 v[100:103], v[188:191], v[156:159], v[100:103]
	v_mfma_f32_16x16x32_bf16 v[96:99], v[196:199], v[156:159], v[96:99]
	v_mfma_f32_16x16x32_bf16 v[80:83], v[196:199], v[152:155], v[80:83]
	v_mfma_f32_16x16x32_bf16 v[84:87], v[188:191], v[152:155], v[84:87]
	s_setprio 0
	s_setprio 1
	v_mfma_f32_16x16x32_bf16 v[124:127], v[168:171], v[148:151], v[124:127]
	v_mfma_f32_16x16x32_bf16 v[120:123], v[176:179], v[148:151], v[120:123]
	v_mfma_f32_16x16x32_bf16 v[104:107], v[176:179], v[144:147], v[104:107]
	v_mfma_f32_16x16x32_bf16 v[108:111], v[168:171], v[144:147], v[108:111]
	v_mfma_f32_16x16x32_bf16 v[92:95], v[168:171], v[140:143], v[92:95]
	v_mfma_f32_16x16x32_bf16 v[88:91], v[176:179], v[140:143], v[88:91]
	v_mfma_f32_16x16x32_bf16 v[72:75], v[176:179], v[136:139], v[72:75]
	v_mfma_f32_16x16x32_bf16 v[76:79], v[168:171], v[136:139], v[76:79]
	v_mfma_f32_16x16x32_bf16 v[124:127], v[172:175], v[164:167], v[124:127]
	v_mfma_f32_16x16x32_bf16 v[120:123], v[180:183], v[164:167], v[120:123]
	v_mfma_f32_16x16x32_bf16 v[104:107], v[180:183], v[160:163], v[104:107]
	v_mfma_f32_16x16x32_bf16 v[108:111], v[172:175], v[160:163], v[108:111]
	v_mfma_f32_16x16x32_bf16 v[92:95], v[172:175], v[156:159], v[92:95]
	v_mfma_f32_16x16x32_bf16 v[88:91], v[180:183], v[156:159], v[88:91]
	v_mfma_f32_16x16x32_bf16 v[72:75], v[180:183], v[152:155], v[72:75]
	v_mfma_f32_16x16x32_bf16 v[76:79], v[172:175], v[152:155], v[76:79]
	s_setprio 0
	s_barrier
	s_and_b64 vcc, exec, s[50:51]
	s_cbranch_vccnz .LBB0_565
	ds_read_b128 v[148:151], v239 offset:49152
	ds_read_b128 v[164:167], v239 offset:50176
	ds_read_b128 v[144:147], v239 offset:51200
	ds_read_b128 v[160:163], v239 offset:52224
	ds_read_b128 v[140:143], v239 offset:53248
	ds_read_b128 v[156:159], v239 offset:54272
	ds_read_b128 v[136:139], v239 offset:55296
	ds_read_b128 v[152:155], v239 offset:56320
.LBB0_565:
	s_mov_b32 m0, s70
	v_lshl_add_u64 v[204:205], v[226:227], 0, s[0:1]
	s_add_u32 s12, s12, 0x20080
	global_load_lds_dwordx4 v[204:205], off
	v_lshl_add_u64 v[204:205], v[228:229], 0, s[0:1]
	s_mov_b32 m0, s71
	s_addc_u32 s13, s13, 0
	global_load_lds_dwordx4 v[204:205], off
	v_lshl_add_u64 v[204:205], s[12:13], 0, v[4:5]
	s_mov_b32 m0, s74
	s_and_b64 vcc, exec, s[50:51]
	global_load_lds_dwordx4 v[204:205], off
	v_lshl_add_u64 v[204:205], s[12:13], 0, v[208:209]
	s_mov_b32 m0, s75
	s_nop 0
	global_load_lds_dwordx4 v[204:205], off
	v_lshl_add_u64 v[204:205], v[230:231], 0, s[0:1]
	s_mov_b32 m0, s72
	s_nop 0
	global_load_lds_dwordx4 v[204:205], off
	v_lshl_add_u64 v[204:205], v[232:233], 0, s[0:1]
	s_mov_b32 m0, s73
	s_nop 0
	global_load_lds_dwordx4 v[204:205], off
	s_waitcnt vmcnt(8)
	s_waitcnt lgkmcnt(0)
	s_barrier
	s_cbranch_vccnz .LBB0_558
	s_setprio 1
	s_waitcnt lgkmcnt(0)
	v_mfma_f32_16x16x32_bf16 v[68:71], v[184:187], v[148:151], v[68:71]
	v_mfma_f32_16x16x32_bf16 v[64:67], v[192:195], v[148:151], v[64:67]
	v_mfma_f32_16x16x32_bf16 v[48:51], v[192:195], v[144:147], v[48:51]
	v_mfma_f32_16x16x32_bf16 v[52:55], v[184:187], v[144:147], v[52:55]
	v_mfma_f32_16x16x32_bf16 v[36:39], v[184:187], v[140:143], v[36:39]
	v_mfma_f32_16x16x32_bf16 v[32:35], v[192:195], v[140:143], v[32:35]
	v_mfma_f32_16x16x32_bf16 v[16:19], v[192:195], v[136:139], v[16:19]
	v_mfma_f32_16x16x32_bf16 v[20:23], v[184:187], v[136:139], v[20:23]
	v_mfma_f32_16x16x32_bf16 v[68:71], v[188:191], v[164:167], v[68:71]
	v_mfma_f32_16x16x32_bf16 v[64:67], v[196:199], v[164:167], v[64:67]
	v_mfma_f32_16x16x32_bf16 v[48:51], v[196:199], v[160:163], v[48:51]
	v_mfma_f32_16x16x32_bf16 v[52:55], v[188:191], v[160:163], v[52:55]
	v_mfma_f32_16x16x32_bf16 v[36:39], v[188:191], v[156:159], v[36:39]
	v_mfma_f32_16x16x32_bf16 v[32:35], v[196:199], v[156:159], v[32:35]
	v_mfma_f32_16x16x32_bf16 v[16:19], v[196:199], v[152:155], v[16:19]
	v_mfma_f32_16x16x32_bf16 v[20:23], v[188:191], v[152:155], v[20:23]
	s_setprio 0
	s_setprio 1
	v_mfma_f32_16x16x32_bf16 v[60:63], v[168:171], v[148:151], v[60:63]
	v_mfma_f32_16x16x32_bf16 v[56:59], v[176:179], v[148:151], v[56:59]
	v_mfma_f32_16x16x32_bf16 v[40:43], v[176:179], v[144:147], v[40:43]
	v_mfma_f32_16x16x32_bf16 v[44:47], v[168:171], v[144:147], v[44:47]
	v_mfma_f32_16x16x32_bf16 v[28:31], v[168:171], v[140:143], v[28:31]
	v_mfma_f32_16x16x32_bf16 v[24:27], v[176:179], v[140:143], v[24:27]
	v_mfma_f32_16x16x32_bf16 v[8:11], v[176:179], v[136:139], v[8:11]
	v_mfma_f32_16x16x32_bf16 v[12:15], v[168:171], v[136:139], v[12:15]
	v_mfma_f32_16x16x32_bf16 v[60:63], v[172:175], v[164:167], v[60:63]
	v_mfma_f32_16x16x32_bf16 v[56:59], v[180:183], v[164:167], v[56:59]
	v_mfma_f32_16x16x32_bf16 v[40:43], v[180:183], v[160:163], v[40:43]
	v_mfma_f32_16x16x32_bf16 v[44:47], v[172:175], v[160:163], v[44:47]
	v_mfma_f32_16x16x32_bf16 v[28:31], v[172:175], v[156:159], v[28:31]
	v_mfma_f32_16x16x32_bf16 v[24:27], v[180:183], v[156:159], v[24:27]
	v_mfma_f32_16x16x32_bf16 v[8:11], v[180:183], v[152:155], v[8:11]
	v_mfma_f32_16x16x32_bf16 v[12:15], v[172:175], v[152:155], v[12:15]
	s_setprio 0
	s_branch .LBB0_558

.LBB0_620:
	s_add_u32 s12, s42, 0xfffe0080
	s_addc_u32 s13, s43, -1
	s_cmp_eq_u32 s57, 4
	s_cselect_b32 s15, s17, s13
	s_cselect_b32 s14, s33, s12
	s_cselect_b32 s13, s11, s27
	s_cselect_b32 s12, s37, s26
	s_add_i32 s58, 0, 0x10000
	v_add_u32_e32 v136, s58, v1
	s_add_i32 s60, 0, 0x14000
	ds_read_b128 v[150:153], v7
	ds_read_b128 v[154:157], v7 offset:1024
	ds_read_b128 v[158:161], v7 offset:2048
	ds_read_b128 v[162:165], v7 offset:3072
	ds_read_b128 v[166:169], v7 offset:4096
	ds_read_b128 v[170:173], v7 offset:5120
	ds_read_b128 v[174:177], v7 offset:6144
	ds_read_b128 v[178:181], v7 offset:7168
	ds_read_b128 v[182:185], v136
	ds_read_b128 v[186:189], v136 offset:1024
	ds_read_b128 v[190:193], v136 offset:2048
	ds_read_b128 v[194:197], v136 offset:3072
	v_add_u32_e32 v136, s60, v1
	ds_read_b128 v[208:211], v136
	ds_read_b128 v[212:215], v136 offset:1024
	ds_read_b128 v[216:219], v136 offset:2048
	ds_read_b128 v[220:223], v136 offset:3072
	v_lshl_add_u64 v[136:137], s[42:43], 0, v[146:147]
	s_add_i32 m0, s38, 0xc000
	s_nop 0
	global_load_lds_dwordx4 v[136:137], off
	v_lshl_add_u64 v[136:137], s[42:43], 0, v[148:149]
	s_add_i32 m0, s38, 0xe000
	s_nop 0
	global_load_lds_dwordx4 v[136:137], off
	s_waitcnt vmcnt(8)
	s_waitcnt lgkmcnt(0)
	s_barrier
	s_setprio 1
	s_waitcnt lgkmcnt(0)
	v_mfma_f32_16x16x32_bf16 v[132:135], v[182:185], v[150:153], v[132:135]
	v_mfma_f32_16x16x32_bf16 v[128:131], v[190:193], v[150:153], v[128:131]
	v_mfma_f32_16x16x32_bf16 v[120:123], v[190:193], v[158:161], v[120:123]
	v_mfma_f32_16x16x32_bf16 v[124:127], v[182:185], v[158:161], v[124:127]
	v_mfma_f32_16x16x32_bf16 v[116:119], v[182:185], v[166:169], v[116:119]
	v_mfma_f32_16x16x32_bf16 v[108:111], v[190:193], v[166:169], v[108:111]
	v_mfma_f32_16x16x32_bf16 v[92:95], v[190:193], v[174:177], v[92:95]
	v_mfma_f32_16x16x32_bf16 v[100:103], v[182:185], v[174:177], v[100:103]
	v_mfma_f32_16x16x32_bf16 v[132:135], v[186:189], v[154:157], v[132:135]
	v_mfma_f32_16x16x32_bf16 v[128:131], v[194:197], v[154:157], v[128:131]
	v_mfma_f32_16x16x32_bf16 v[120:123], v[194:197], v[162:165], v[120:123]
	v_mfma_f32_16x16x32_bf16 v[124:127], v[186:189], v[162:165], v[124:127]
	v_mfma_f32_16x16x32_bf16 v[116:119], v[186:189], v[170:173], v[116:119]
	v_mfma_f32_16x16x32_bf16 v[108:111], v[194:197], v[170:173], v[108:111]
	v_mfma_f32_16x16x32_bf16 v[92:95], v[194:197], v[178:181], v[92:95]
	v_mfma_f32_16x16x32_bf16 v[100:103], v[186:189], v[178:181], v[100:103]
	s_setprio 0
	s_setprio 1
	v_mfma_f32_16x16x32_bf16 v[112:115], v[208:211], v[150:153], v[112:115]
	v_mfma_f32_16x16x32_bf16 v[104:107], v[216:219], v[150:153], v[104:107]
	v_mfma_f32_16x16x32_bf16 v[88:91], v[216:219], v[158:161], v[88:91]
	v_mfma_f32_16x16x32_bf16 v[96:99], v[208:211], v[158:161], v[96:99]
	v_mfma_f32_16x16x32_bf16 v[84:87], v[208:211], v[166:169], v[84:87]
	v_mfma_f32_16x16x32_bf16 v[80:83], v[216:219], v[166:169], v[80:83]
	v_mfma_f32_16x16x32_bf16 v[72:75], v[216:219], v[174:177], v[72:75]
	v_mfma_f32_16x16x32_bf16 v[76:79], v[208:211], v[174:177], v[76:79]
	v_mfma_f32_16x16x32_bf16 v[112:115], v[212:215], v[154:157], v[112:115]
	v_mfma_f32_16x16x32_bf16 v[104:107], v[220:223], v[154:157], v[104:107]
	v_mfma_f32_16x16x32_bf16 v[88:91], v[220:223], v[162:165], v[88:91]
	v_mfma_f32_16x16x32_bf16 v[96:99], v[212:215], v[162:165], v[96:99]
	v_mfma_f32_16x16x32_bf16 v[84:87], v[212:215], v[170:173], v[84:87]
	v_mfma_f32_16x16x32_bf16 v[80:83], v[220:223], v[170:173], v[80:83]
	v_mfma_f32_16x16x32_bf16 v[72:75], v[220:223], v[178:181], v[72:75]
	v_mfma_f32_16x16x32_bf16 v[76:79], v[212:215], v[178:181], v[76:79]
	s_setprio 0
	s_barrier
	s_add_i32 s58, s58, s35
	v_lshl_add_u64 v[136:137], s[12:13], 0, v[2:3]
	s_mov_b32 m0, s58
	ds_read_b128 v[150:153], v7 offset:16384
	ds_read_b128 v[154:157], v7 offset:17408
	ds_read_b128 v[158:161], v7 offset:18432
	ds_read_b128 v[162:165], v7 offset:19456
	ds_read_b128 v[166:169], v7 offset:20480
	ds_read_b128 v[170:173], v7 offset:21504
	ds_read_b128 v[174:177], v7 offset:22528
	ds_read_b128 v[178:181], v7 offset:23552
	global_load_lds_dwordx4 v[136:137], off
	s_add_i32 m0, s58, 0x2000
	s_add_u32 s58, s12, 0x20000
	v_lshl_add_u64 v[198:199], s[12:13], 0, v[4:5]
	s_addc_u32 s59, s13, 0
	s_add_i32 s60, s60, s35
	global_load_lds_dwordx4 v[198:199], off
	v_lshl_add_u64 v[204:205], s[58:59], 0, v[2:3]
	s_mov_b32 m0, s60
	v_lshl_add_u64 v[224:225], s[14:15], 0, v[138:139]
	global_load_lds_dwordx4 v[204:205], off
	v_lshl_add_u64 v[204:205], s[58:59], 0, v[4:5]
	s_add_i32 m0, s60, 0x2000
	s_nop 0
	global_load_lds_dwordx4 v[204:205], off
	v_lshl_add_u64 v[204:205], s[14:15], 0, v[140:141]
	s_mov_b32 m0, s38
	s_nop 0
	global_load_lds_dwordx4 v[204:205], off
	s_mov_b32 m0, s39
	s_nop 0
	global_load_lds_dwordx4 v[224:225], off
	s_waitcnt vmcnt(8)
	s_waitcnt lgkmcnt(0)
	s_barrier
	s_setprio 1
	s_waitcnt lgkmcnt(0)
	v_mfma_f32_16x16x32_bf16 v[68:71], v[182:185], v[150:153], v[68:71]
	v_mfma_f32_16x16x32_bf16 v[64:67], v[190:193], v[150:153], v[64:67]
	v_mfma_f32_16x16x32_bf16 v[56:59], v[190:193], v[158:161], v[56:59]
	v_mfma_f32_16x16x32_bf16 v[60:63], v[182:185], v[158:161], v[60:63]
	v_mfma_f32_16x16x32_bf16 v[52:55], v[182:185], v[166:169], v[52:55]
	v_mfma_f32_16x16x32_bf16 v[44:47], v[190:193], v[166:169], v[44:47]
	v_mfma_f32_16x16x32_bf16 v[28:31], v[190:193], v[174:177], v[28:31]
	v_mfma_f32_16x16x32_bf16 v[36:39], v[182:185], v[174:177], v[36:39]
	v_mfma_f32_16x16x32_bf16 v[68:71], v[186:189], v[154:157], v[68:71]
	v_mfma_f32_16x16x32_bf16 v[64:67], v[194:197], v[154:157], v[64:67]
	v_mfma_f32_16x16x32_bf16 v[56:59], v[194:197], v[162:165], v[56:59]
	v_mfma_f32_16x16x32_bf16 v[60:63], v[186:189], v[162:165], v[60:63]
	v_mfma_f32_16x16x32_bf16 v[52:55], v[186:189], v[170:173], v[52:55]
	v_mfma_f32_16x16x32_bf16 v[44:47], v[194:197], v[170:173], v[44:47]
	v_mfma_f32_16x16x32_bf16 v[28:31], v[194:197], v[178:181], v[28:31]
	v_mfma_f32_16x16x32_bf16 v[36:39], v[186:189], v[178:181], v[36:39]
	s_setprio 0
	s_setprio 1
	v_mfma_f32_16x16x32_bf16 v[48:51], v[208:211], v[150:153], v[48:51]
	v_mfma_f32_16x16x32_bf16 v[40:43], v[216:219], v[150:153], v[40:43]
	v_mfma_f32_16x16x32_bf16 v[24:27], v[216:219], v[158:161], v[24:27]
	v_mfma_f32_16x16x32_bf16 v[32:35], v[208:211], v[158:161], v[32:35]
	v_mfma_f32_16x16x32_bf16 v[20:23], v[208:211], v[166:169], v[20:23]
	v_mfma_f32_16x16x32_bf16 v[16:19], v[216:219], v[166:169], v[16:19]
	v_mfma_f32_16x16x32_bf16 v[8:11], v[216:219], v[174:177], v[8:11]
	v_mfma_f32_16x16x32_bf16 v[12:15], v[208:211], v[174:177], v[12:15]
	v_mfma_f32_16x16x32_bf16 v[48:51], v[212:215], v[154:157], v[48:51]
	v_mfma_f32_16x16x32_bf16 v[40:43], v[220:223], v[154:157], v[40:43]
	v_mfma_f32_16x16x32_bf16 v[24:27], v[220:223], v[162:165], v[24:27]
	v_mfma_f32_16x16x32_bf16 v[32:35], v[212:215], v[162:165], v[32:35]
	v_mfma_f32_16x16x32_bf16 v[20:23], v[212:215], v[170:173], v[20:23]
	v_mfma_f32_16x16x32_bf16 v[16:19], v[220:223], v[170:173], v[16:19]
	v_mfma_f32_16x16x32_bf16 v[8:11], v[220:223], v[178:181], v[8:11]
	v_mfma_f32_16x16x32_bf16 v[12:15], v[212:215], v[178:181], v[12:15]
	s_setprio 0
	s_barrier
	s_add_i32 s58, 0, 0x18000
	s_add_i32 s59, 0, 0x1c000
	s_add_u32 s14, s14, 0x20000
	s_addc_u32 s15, s15, 0
	s_mov_b32 m0, s40
	v_add_u32_e32 v194, s58, v1
	v_add_u32_e32 v207, s59, v1
	v_lshl_add_u64 v[226:227], s[14:15], 0, v[140:141]
	ds_read_b128 v[150:153], v7 offset:32768
	ds_read_b128 v[154:157], v7 offset:33792
	ds_read_b128 v[158:161], v7 offset:34816
	ds_read_b128 v[162:165], v7 offset:35840
	ds_read_b128 v[166:169], v7 offset:36864
	ds_read_b128 v[170:173], v7 offset:37888
	ds_read_b128 v[174:177], v7 offset:38912
	ds_read_b128 v[178:181], v7 offset:39936
	ds_read_b128 v[182:185], v194
	ds_read_b128 v[186:189], v194 offset:1024
	ds_read_b128 v[190:193], v194 offset:2048
	ds_read_b128 v[194:197], v194 offset:3072
	ds_read_b128 v[208:211], v207
	ds_read_b128 v[212:215], v207 offset:1024
	ds_read_b128 v[216:219], v207 offset:2048
	ds_read_b128 v[220:223], v207 offset:3072
	global_load_lds_dwordx4 v[226:227], off
	v_lshl_add_u64 v[226:227], s[14:15], 0, v[138:139]
	s_mov_b32 m0, s41
	s_nop 0
	global_load_lds_dwordx4 v[226:227], off
	s_waitcnt vmcnt(8)
	s_waitcnt lgkmcnt(0)
	s_barrier
	s_setprio 1
	s_waitcnt lgkmcnt(0)
	v_mfma_f32_16x16x32_bf16 v[132:135], v[182:185], v[150:153], v[132:135]
	v_mfma_f32_16x16x32_bf16 v[128:131], v[190:193], v[150:153], v[128:131]
	v_mfma_f32_16x16x32_bf16 v[120:123], v[190:193], v[158:161], v[120:123]
	v_mfma_f32_16x16x32_bf16 v[124:127], v[182:185], v[158:161], v[124:127]
	v_mfma_f32_16x16x32_bf16 v[116:119], v[182:185], v[166:169], v[116:119]
	v_mfma_f32_16x16x32_bf16 v[108:111], v[190:193], v[166:169], v[108:111]
	v_mfma_f32_16x16x32_bf16 v[92:95], v[190:193], v[174:177], v[92:95]
	v_mfma_f32_16x16x32_bf16 v[100:103], v[182:185], v[174:177], v[100:103]
	v_mfma_f32_16x16x32_bf16 v[132:135], v[186:189], v[154:157], v[132:135]
	v_mfma_f32_16x16x32_bf16 v[128:131], v[194:197], v[154:157], v[128:131]
	v_mfma_f32_16x16x32_bf16 v[120:123], v[194:197], v[162:165], v[120:123]
	v_mfma_f32_16x16x32_bf16 v[124:127], v[186:189], v[162:165], v[124:127]
	v_mfma_f32_16x16x32_bf16 v[116:119], v[186:189], v[170:173], v[116:119]
	v_mfma_f32_16x16x32_bf16 v[108:111], v[194:197], v[170:173], v[108:111]
	v_mfma_f32_16x16x32_bf16 v[92:95], v[194:197], v[178:181], v[92:95]
	v_mfma_f32_16x16x32_bf16 v[100:103], v[186:189], v[178:181], v[100:103]
	s_setprio 0
	s_setprio 1
	v_mfma_f32_16x16x32_bf16 v[112:115], v[208:211], v[150:153], v[112:115]
	v_mfma_f32_16x16x32_bf16 v[104:107], v[216:219], v[150:153], v[104:107]
	v_mfma_f32_16x16x32_bf16 v[88:91], v[216:219], v[158:161], v[88:91]
	v_mfma_f32_16x16x32_bf16 v[96:99], v[208:211], v[158:161], v[96:99]
	v_mfma_f32_16x16x32_bf16 v[84:87], v[208:211], v[166:169], v[84:87]
	v_mfma_f32_16x16x32_bf16 v[80:83], v[216:219], v[166:169], v[80:83]
	v_mfma_f32_16x16x32_bf16 v[72:75], v[216:219], v[174:177], v[72:75]
	v_mfma_f32_16x16x32_bf16 v[76:79], v[208:211], v[174:177], v[76:79]
	v_mfma_f32_16x16x32_bf16 v[112:115], v[212:215], v[154:157], v[112:115]
	v_mfma_f32_16x16x32_bf16 v[104:107], v[220:223], v[154:157], v[104:107]
	v_mfma_f32_16x16x32_bf16 v[88:91], v[220:223], v[162:165], v[88:91]
	v_mfma_f32_16x16x32_bf16 v[96:99], v[212:215], v[162:165], v[96:99]
	v_mfma_f32_16x16x32_bf16 v[84:87], v[212:215], v[170:173], v[84:87]
	v_mfma_f32_16x16x32_bf16 v[80:83], v[220:223], v[170:173], v[80:83]
	v_mfma_f32_16x16x32_bf16 v[72:75], v[220:223], v[178:181], v[72:75]
	v_mfma_f32_16x16x32_bf16 v[76:79], v[212:215], v[178:181], v[76:79]
	s_setprio 0
	s_barrier
	s_add_i32 s14, s58, s35
	v_lshl_add_u64 v[136:137], v[136:137], 0, s[0:1]
	s_mov_b32 m0, s14
	ds_read_b128 v[150:153], v7 offset:49152
	ds_read_b128 v[154:157], v7 offset:50176
	ds_read_b128 v[158:161], v7 offset:51200
	ds_read_b128 v[162:165], v7 offset:52224
	ds_read_b128 v[166:169], v7 offset:53248
	ds_read_b128 v[170:173], v7 offset:54272
	ds_read_b128 v[174:177], v7 offset:55296
	ds_read_b128 v[178:181], v7 offset:56320
	global_load_lds_dwordx4 v[136:137], off
	s_add_i32 m0, s14, 0x2000
	s_add_u32 s12, s12, 0x20080
	v_lshl_add_u64 v[136:137], v[198:199], 0, s[0:1]
	s_addc_u32 s13, s13, 0
	s_add_i32 s14, s59, s35
	global_load_lds_dwordx4 v[136:137], off
	v_lshl_add_u64 v[136:137], s[12:13], 0, v[2:3]
	s_mov_b32 m0, s14
	s_nop 0
	global_load_lds_dwordx4 v[136:137], off
	v_lshl_add_u64 v[136:137], s[12:13], 0, v[4:5]
	s_add_i32 m0, s14, 0x2000
	s_nop 0
	global_load_lds_dwordx4 v[136:137], off
	v_lshl_add_u64 v[136:137], v[204:205], 0, s[0:1]
	s_mov_b32 m0, s49
	s_nop 0
	global_load_lds_dwordx4 v[136:137], off
	v_lshl_add_u64 v[136:137], v[224:225], 0, s[0:1]
	s_mov_b32 m0, s52
	s_nop 0
	global_load_lds_dwordx4 v[136:137], off
	s_waitcnt vmcnt(8)
	s_waitcnt lgkmcnt(0)
	s_barrier
	s_setprio 1
	s_waitcnt lgkmcnt(0)
	v_mfma_f32_16x16x32_bf16 v[68:71], v[182:185], v[150:153], v[68:71]
	v_mfma_f32_16x16x32_bf16 v[64:67], v[190:193], v[150:153], v[64:67]
	v_mfma_f32_16x16x32_bf16 v[56:59], v[190:193], v[158:161], v[56:59]
	v_mfma_f32_16x16x32_bf16 v[60:63], v[182:185], v[158:161], v[60:63]
	v_mfma_f32_16x16x32_bf16 v[52:55], v[182:185], v[166:169], v[52:55]
	v_mfma_f32_16x16x32_bf16 v[44:47], v[190:193], v[166:169], v[44:47]
	v_mfma_f32_16x16x32_bf16 v[28:31], v[190:193], v[174:177], v[28:31]
	v_mfma_f32_16x16x32_bf16 v[36:39], v[182:185], v[174:177], v[36:39]
	v_mfma_f32_16x16x32_bf16 v[68:71], v[186:189], v[154:157], v[68:71]
	v_mfma_f32_16x16x32_bf16 v[64:67], v[194:197], v[154:157], v[64:67]
	v_mfma_f32_16x16x32_bf16 v[56:59], v[194:197], v[162:165], v[56:59]
	v_mfma_f32_16x16x32_bf16 v[60:63], v[186:189], v[162:165], v[60:63]
	v_mfma_f32_16x16x32_bf16 v[52:55], v[186:189], v[170:173], v[52:55]
	v_mfma_f32_16x16x32_bf16 v[44:47], v[194:197], v[170:173], v[44:47]
	v_mfma_f32_16x16x32_bf16 v[28:31], v[194:197], v[178:181], v[28:31]
	v_mfma_f32_16x16x32_bf16 v[36:39], v[186:189], v[178:181], v[36:39]
	s_setprio 0
	s_setprio 1
	v_mfma_f32_16x16x32_bf16 v[48:51], v[208:211], v[150:153], v[48:51]
	v_mfma_f32_16x16x32_bf16 v[40:43], v[216:219], v[150:153], v[40:43]
	v_mfma_f32_16x16x32_bf16 v[24:27], v[216:219], v[158:161], v[24:27]
	v_mfma_f32_16x16x32_bf16 v[32:35], v[208:211], v[158:161], v[32:35]
	v_mfma_f32_16x16x32_bf16 v[20:23], v[208:211], v[166:169], v[20:23]
	v_mfma_f32_16x16x32_bf16 v[16:19], v[216:219], v[166:169], v[16:19]
	v_mfma_f32_16x16x32_bf16 v[8:11], v[216:219], v[174:177], v[8:11]
	v_mfma_f32_16x16x32_bf16 v[12:15], v[208:211], v[174:177], v[12:15]
	v_mfma_f32_16x16x32_bf16 v[48:51], v[212:215], v[154:157], v[48:51]
	v_mfma_f32_16x16x32_bf16 v[40:43], v[220:223], v[154:157], v[40:43]
	v_mfma_f32_16x16x32_bf16 v[24:27], v[220:223], v[162:165], v[24:27]
	v_mfma_f32_16x16x32_bf16 v[32:35], v[212:215], v[162:165], v[32:35]
	v_mfma_f32_16x16x32_bf16 v[20:23], v[212:215], v[170:173], v[20:23]
	v_mfma_f32_16x16x32_bf16 v[16:19], v[220:223], v[170:173], v[16:19]
	v_mfma_f32_16x16x32_bf16 v[8:11], v[220:223], v[178:181], v[8:11]
	v_mfma_f32_16x16x32_bf16 v[12:15], v[212:215], v[178:181], v[12:15]
	s_setprio 0
	s_barrier
	s_add_i32 s57, s57, 2
	s_add_u32 s42, s42, 0x100
	s_addc_u32 s43, s43, 0
	s_add_u32 s26, s26, 0x100
	s_addc_u32 s27, s27, 0
	s_cmp_gt_u32 s57, 5
	s_cbranch_scc0 .LBB0_620
	s_and_b64 vcc, exec, s[6:7]
	s_cbranch_vccz .LBB0_623
	s_barrier

.LBB0_986:
	s_add_u32 s12, s44, 0xfff80080
	s_addc_u32 s13, s45, -1
	s_cmp_eq_u32 s50, 28
	s_cselect_b32 s15, s18, s13
	s_cselect_b32 s14, s19, s12
	s_cselect_b32 s13, s17, s43
	s_cselect_b32 s12, s21, s33
	s_add_i32 s51, 0, 0x10000
	v_add_u32_e32 v2, s51, v7
	s_add_i32 s63, 0, 0x14000
	ds_read_b128 v[150:153], v155
	ds_read_b128 v[156:159], v155 offset:1024
	ds_read_b128 v[160:163], v155 offset:2048
	ds_read_b128 v[164:167], v155 offset:3072
	ds_read_b128 v[168:171], v155 offset:4096
	ds_read_b128 v[172:175], v155 offset:5120
	ds_read_b128 v[176:179], v155 offset:6144
	ds_read_b128 v[180:183], v155 offset:7168
	ds_read_b128 v[184:187], v2
	ds_read_b128 v[188:191], v2 offset:1024
	ds_read_b128 v[192:195], v2 offset:2048
	ds_read_b128 v[196:199], v2 offset:3072
	v_add_u32_e32 v2, s63, v7
	v_lshl_add_u64 v[224:225], s[44:45], 0, v[146:147]
	s_add_i32 m0, s39, 0xc000
	ds_read_b128 v[208:211], v2
	ds_read_b128 v[212:215], v2 offset:1024
	ds_read_b128 v[216:219], v2 offset:2048
	ds_read_b128 v[220:223], v2 offset:3072
	global_load_lds_dwordx4 v[224:225], off
	v_lshl_add_u64 v[224:225], s[44:45], 0, v[148:149]
	s_add_i32 m0, s39, 0xe000
	s_nop 0
	global_load_lds_dwordx4 v[224:225], off
	s_waitcnt vmcnt(8)
	s_waitcnt lgkmcnt(0)
	s_barrier
	s_setprio 1
	s_waitcnt lgkmcnt(0)
	v_mfma_f32_16x16x32_bf16 v[132:135], v[184:187], v[150:153], v[132:135]
	v_mfma_f32_16x16x32_bf16 v[128:131], v[192:195], v[150:153], v[128:131]
	v_mfma_f32_16x16x32_bf16 v[112:115], v[192:195], v[160:163], v[112:115]
	v_mfma_f32_16x16x32_bf16 v[116:119], v[184:187], v[160:163], v[116:119]
	v_mfma_f32_16x16x32_bf16 v[100:103], v[184:187], v[168:171], v[100:103]
	v_mfma_f32_16x16x32_bf16 v[96:99], v[192:195], v[168:171], v[96:99]
	v_mfma_f32_16x16x32_bf16 v[80:83], v[192:195], v[176:179], v[80:83]
	v_mfma_f32_16x16x32_bf16 v[84:87], v[184:187], v[176:179], v[84:87]
	v_mfma_f32_16x16x32_bf16 v[132:135], v[188:191], v[156:159], v[132:135]
	v_mfma_f32_16x16x32_bf16 v[128:131], v[196:199], v[156:159], v[128:131]
	v_mfma_f32_16x16x32_bf16 v[112:115], v[196:199], v[164:167], v[112:115]
	v_mfma_f32_16x16x32_bf16 v[116:119], v[188:191], v[164:167], v[116:119]
	v_mfma_f32_16x16x32_bf16 v[100:103], v[188:191], v[172:175], v[100:103]
	v_mfma_f32_16x16x32_bf16 v[96:99], v[196:199], v[172:175], v[96:99]
	v_mfma_f32_16x16x32_bf16 v[80:83], v[196:199], v[180:183], v[80:83]
	v_mfma_f32_16x16x32_bf16 v[84:87], v[188:191], v[180:183], v[84:87]
	s_setprio 0
	s_setprio 1
	v_mfma_f32_16x16x32_bf16 v[124:127], v[208:211], v[150:153], v[124:127]
	v_mfma_f32_16x16x32_bf16 v[120:123], v[216:219], v[150:153], v[120:123]
	v_mfma_f32_16x16x32_bf16 v[104:107], v[216:219], v[160:163], v[104:107]
	v_mfma_f32_16x16x32_bf16 v[108:111], v[208:211], v[160:163], v[108:111]
	v_mfma_f32_16x16x32_bf16 v[92:95], v[208:211], v[168:171], v[92:95]
	v_mfma_f32_16x16x32_bf16 v[88:91], v[216:219], v[168:171], v[88:91]
	v_mfma_f32_16x16x32_bf16 v[72:75], v[216:219], v[176:179], v[72:75]
	v_mfma_f32_16x16x32_bf16 v[76:79], v[208:211], v[176:179], v[76:79]
	v_mfma_f32_16x16x32_bf16 v[124:127], v[212:215], v[156:159], v[124:127]
	v_mfma_f32_16x16x32_bf16 v[120:123], v[220:223], v[156:159], v[120:123]
	v_mfma_f32_16x16x32_bf16 v[104:107], v[220:223], v[164:167], v[104:107]
	v_mfma_f32_16x16x32_bf16 v[108:111], v[212:215], v[164:167], v[108:111]
	v_mfma_f32_16x16x32_bf16 v[92:95], v[212:215], v[172:175], v[92:95]
	v_mfma_f32_16x16x32_bf16 v[88:91], v[220:223], v[172:175], v[88:91]
	v_mfma_f32_16x16x32_bf16 v[72:75], v[220:223], v[180:183], v[72:75]
	v_mfma_f32_16x16x32_bf16 v[76:79], v[212:215], v[180:183], v[76:79]
	s_setprio 0
	s_barrier
	s_add_i32 s51, s51, s38
	v_lshl_add_u64 v[224:225], s[12:13], 0, v[138:139]
	s_mov_b32 m0, s51
	ds_read_b128 v[150:153], v155 offset:16384
	ds_read_b128 v[156:159], v155 offset:17408
	ds_read_b128 v[160:163], v155 offset:18432
	ds_read_b128 v[164:167], v155 offset:19456
	ds_read_b128 v[168:171], v155 offset:20480
	ds_read_b128 v[172:175], v155 offset:21504
	ds_read_b128 v[176:179], v155 offset:22528
	ds_read_b128 v[180:183], v155 offset:23552
	global_load_lds_dwordx4 v[224:225], off
	s_add_i32 m0, s51, 0x2000
	s_add_u32 s64, s12, 0x80000
	v_lshl_add_u64 v[226:227], s[12:13], 0, v[4:5]
	s_addc_u32 s65, s13, 0
	s_add_i32 s51, s63, s38
	global_load_lds_dwordx4 v[226:227], off
	v_lshl_add_u64 v[228:229], s[64:65], 0, v[138:139]
	s_mov_b32 m0, s51
	v_lshl_add_u64 v[230:231], s[14:15], 0, v[136:137]
	global_load_lds_dwordx4 v[228:229], off
	v_lshl_add_u64 v[228:229], s[64:65], 0, v[4:5]
	s_add_i32 m0, s51, 0x2000
	s_nop 0
	global_load_lds_dwordx4 v[228:229], off
	v_lshl_add_u64 v[228:229], s[14:15], 0, v[140:141]
	s_mov_b32 m0, s39
	s_nop 0
	global_load_lds_dwordx4 v[228:229], off
	s_mov_b32 m0, s40
	s_nop 0
	global_load_lds_dwordx4 v[230:231], off
	s_waitcnt vmcnt(8)
	s_waitcnt lgkmcnt(0)
	s_barrier
	s_setprio 1
	s_waitcnt lgkmcnt(0)
	v_mfma_f32_16x16x32_bf16 v[68:71], v[184:187], v[150:153], v[68:71]
	v_mfma_f32_16x16x32_bf16 v[64:67], v[192:195], v[150:153], v[64:67]
	v_mfma_f32_16x16x32_bf16 v[48:51], v[192:195], v[160:163], v[48:51]
	v_mfma_f32_16x16x32_bf16 v[52:55], v[184:187], v[160:163], v[52:55]
	v_mfma_f32_16x16x32_bf16 v[36:39], v[184:187], v[168:171], v[36:39]
	v_mfma_f32_16x16x32_bf16 v[32:35], v[192:195], v[168:171], v[32:35]
	v_mfma_f32_16x16x32_bf16 v[16:19], v[192:195], v[176:179], v[16:19]
	v_mfma_f32_16x16x32_bf16 v[20:23], v[184:187], v[176:179], v[20:23]
	v_mfma_f32_16x16x32_bf16 v[68:71], v[188:191], v[156:159], v[68:71]
	v_mfma_f32_16x16x32_bf16 v[64:67], v[196:199], v[156:159], v[64:67]
	v_mfma_f32_16x16x32_bf16 v[48:51], v[196:199], v[164:167], v[48:51]
	v_mfma_f32_16x16x32_bf16 v[52:55], v[188:191], v[164:167], v[52:55]
	v_mfma_f32_16x16x32_bf16 v[36:39], v[188:191], v[172:175], v[36:39]
	v_mfma_f32_16x16x32_bf16 v[32:35], v[196:199], v[172:175], v[32:35]
	v_mfma_f32_16x16x32_bf16 v[16:19], v[196:199], v[180:183], v[16:19]
	v_mfma_f32_16x16x32_bf16 v[20:23], v[188:191], v[180:183], v[20:23]
	s_setprio 0
	s_setprio 1
	v_mfma_f32_16x16x32_bf16 v[60:63], v[208:211], v[150:153], v[60:63]
	v_mfma_f32_16x16x32_bf16 v[56:59], v[216:219], v[150:153], v[56:59]
	v_mfma_f32_16x16x32_bf16 v[40:43], v[216:219], v[160:163], v[40:43]
	v_mfma_f32_16x16x32_bf16 v[44:47], v[208:211], v[160:163], v[44:47]
	v_mfma_f32_16x16x32_bf16 v[28:31], v[208:211], v[168:171], v[28:31]
	v_mfma_f32_16x16x32_bf16 v[24:27], v[216:219], v[168:171], v[24:27]
	v_mfma_f32_16x16x32_bf16 v[8:11], v[216:219], v[176:179], v[8:11]
	v_mfma_f32_16x16x32_bf16 v[12:15], v[208:211], v[176:179], v[12:15]
	v_mfma_f32_16x16x32_bf16 v[60:63], v[212:215], v[156:159], v[60:63]
	v_mfma_f32_16x16x32_bf16 v[56:59], v[220:223], v[156:159], v[56:59]
	v_mfma_f32_16x16x32_bf16 v[40:43], v[220:223], v[164:167], v[40:43]
	v_mfma_f32_16x16x32_bf16 v[44:47], v[212:215], v[164:167], v[44:47]
	v_mfma_f32_16x16x32_bf16 v[28:31], v[212:215], v[172:175], v[28:31]
	v_mfma_f32_16x16x32_bf16 v[24:27], v[220:223], v[172:175], v[24:27]
	v_mfma_f32_16x16x32_bf16 v[8:11], v[220:223], v[180:183], v[8:11]
	v_mfma_f32_16x16x32_bf16 v[12:15], v[212:215], v[180:183], v[12:15]
	s_setprio 0
	s_barrier
	s_add_i32 s51, 0, 0x18000
	s_add_i32 s63, 0, 0x1c000
	s_add_u32 s14, s14, 0x80000
	v_add_u32_e32 v2, s51, v7
	s_addc_u32 s15, s15, 0
	s_mov_b32 m0, s41
	ds_read_b128 v[150:153], v155 offset:32768
	ds_read_b128 v[156:159], v155 offset:33792
	ds_read_b128 v[160:163], v155 offset:34816
	ds_read_b128 v[164:167], v155 offset:35840
	ds_read_b128 v[168:171], v155 offset:36864
	ds_read_b128 v[172:175], v155 offset:37888
	ds_read_b128 v[176:179], v155 offset:38912
	ds_read_b128 v[180:183], v155 offset:39936
	ds_read_b128 v[184:187], v2
	ds_read_b128 v[188:191], v2 offset:1024
	ds_read_b128 v[192:195], v2 offset:2048
	ds_read_b128 v[196:199], v2 offset:3072
	v_add_u32_e32 v2, s63, v7
	v_lshl_add_u64 v[232:233], s[14:15], 0, v[140:141]
	ds_read_b128 v[208:211], v2
	ds_read_b128 v[212:215], v2 offset:1024
	ds_read_b128 v[216:219], v2 offset:2048
	ds_read_b128 v[220:223], v2 offset:3072
	global_load_lds_dwordx4 v[232:233], off
	v_lshl_add_u64 v[232:233], s[14:15], 0, v[136:137]
	s_mov_b32 m0, s47
	s_nop 0
	global_load_lds_dwordx4 v[232:233], off
	s_waitcnt vmcnt(8)
	s_waitcnt lgkmcnt(0)
	s_barrier
	s_setprio 1
	s_waitcnt lgkmcnt(0)
	v_mfma_f32_16x16x32_bf16 v[132:135], v[184:187], v[150:153], v[132:135]
	v_mfma_f32_16x16x32_bf16 v[128:131], v[192:195], v[150:153], v[128:131]
	v_mfma_f32_16x16x32_bf16 v[112:115], v[192:195], v[160:163], v[112:115]
	v_mfma_f32_16x16x32_bf16 v[116:119], v[184:187], v[160:163], v[116:119]
	v_mfma_f32_16x16x32_bf16 v[100:103], v[184:187], v[168:171], v[100:103]
	v_mfma_f32_16x16x32_bf16 v[96:99], v[192:195], v[168:171], v[96:99]
	v_mfma_f32_16x16x32_bf16 v[80:83], v[192:195], v[176:179], v[80:83]
	v_mfma_f32_16x16x32_bf16 v[84:87], v[184:187], v[176:179], v[84:87]
	v_mfma_f32_16x16x32_bf16 v[132:135], v[188:191], v[156:159], v[132:135]
	v_mfma_f32_16x16x32_bf16 v[128:131], v[196:199], v[156:159], v[128:131]
	v_mfma_f32_16x16x32_bf16 v[112:115], v[196:199], v[164:167], v[112:115]
	v_mfma_f32_16x16x32_bf16 v[116:119], v[188:191], v[164:167], v[116:119]
	v_mfma_f32_16x16x32_bf16 v[100:103], v[188:191], v[172:175], v[100:103]
	v_mfma_f32_16x16x32_bf16 v[96:99], v[196:199], v[172:175], v[96:99]
	v_mfma_f32_16x16x32_bf16 v[80:83], v[196:199], v[180:183], v[80:83]
	v_mfma_f32_16x16x32_bf16 v[84:87], v[188:191], v[180:183], v[84:87]
	s_setprio 0
	s_setprio 1
	v_mfma_f32_16x16x32_bf16 v[124:127], v[208:211], v[150:153], v[124:127]
	v_mfma_f32_16x16x32_bf16 v[120:123], v[216:219], v[150:153], v[120:123]
	v_mfma_f32_16x16x32_bf16 v[104:107], v[216:219], v[160:163], v[104:107]
	v_mfma_f32_16x16x32_bf16 v[108:111], v[208:211], v[160:163], v[108:111]
	v_mfma_f32_16x16x32_bf16 v[92:95], v[208:211], v[168:171], v[92:95]
	v_mfma_f32_16x16x32_bf16 v[88:91], v[216:219], v[168:171], v[88:91]
	v_mfma_f32_16x16x32_bf16 v[72:75], v[216:219], v[176:179], v[72:75]
	v_mfma_f32_16x16x32_bf16 v[76:79], v[208:211], v[176:179], v[76:79]
	v_mfma_f32_16x16x32_bf16 v[124:127], v[212:215], v[156:159], v[124:127]
	v_mfma_f32_16x16x32_bf16 v[120:123], v[220:223], v[156:159], v[120:123]
	v_mfma_f32_16x16x32_bf16 v[104:107], v[220:223], v[164:167], v[104:107]
	v_mfma_f32_16x16x32_bf16 v[108:111], v[212:215], v[164:167], v[108:111]
	v_mfma_f32_16x16x32_bf16 v[92:95], v[212:215], v[172:175], v[92:95]
	v_mfma_f32_16x16x32_bf16 v[88:91], v[220:223], v[172:175], v[88:91]
	v_mfma_f32_16x16x32_bf16 v[72:75], v[220:223], v[180:183], v[72:75]
	v_mfma_f32_16x16x32_bf16 v[76:79], v[212:215], v[180:183], v[76:79]
	s_setprio 0
	s_barrier
	s_add_i32 s14, s51, s38
	v_lshl_add_u64 v[224:225], v[224:225], 0, s[0:1]
	s_mov_b32 m0, s14
	ds_read_b128 v[150:153], v155 offset:49152
	ds_read_b128 v[156:159], v155 offset:50176
	ds_read_b128 v[160:163], v155 offset:51200
	ds_read_b128 v[164:167], v155 offset:52224
	ds_read_b128 v[168:171], v155 offset:53248
	ds_read_b128 v[172:175], v155 offset:54272
	ds_read_b128 v[176:179], v155 offset:55296
	ds_read_b128 v[180:183], v155 offset:56320
	global_load_lds_dwordx4 v[224:225], off
	s_add_i32 m0, s14, 0x2000
	s_add_u32 s12, s12, 0x80080
	v_lshl_add_u64 v[224:225], v[226:227], 0, s[0:1]
	s_addc_u32 s13, s13, 0
	s_add_i32 s14, s63, s38
	global_load_lds_dwordx4 v[224:225], off
	v_lshl_add_u64 v[224:225], s[12:13], 0, v[138:139]
	s_mov_b32 m0, s14
	s_nop 0
	global_load_lds_dwordx4 v[224:225], off
	v_lshl_add_u64 v[224:225], s[12:13], 0, v[4:5]
	s_add_i32 m0, s14, 0x2000
	s_nop 0
	global_load_lds_dwordx4 v[224:225], off
	v_lshl_add_u64 v[224:225], v[228:229], 0, s[0:1]
	s_mov_b32 m0, s60
	s_nop 0
	global_load_lds_dwordx4 v[224:225], off
	v_lshl_add_u64 v[224:225], v[230:231], 0, s[0:1]
	s_mov_b32 m0, s61
	s_nop 0
	global_load_lds_dwordx4 v[224:225], off
	s_waitcnt vmcnt(8)
	s_waitcnt lgkmcnt(0)
	s_barrier
	s_setprio 1
	s_waitcnt lgkmcnt(0)
	v_mfma_f32_16x16x32_bf16 v[68:71], v[184:187], v[150:153], v[68:71]
	v_mfma_f32_16x16x32_bf16 v[64:67], v[192:195], v[150:153], v[64:67]
	v_mfma_f32_16x16x32_bf16 v[48:51], v[192:195], v[160:163], v[48:51]
	v_mfma_f32_16x16x32_bf16 v[52:55], v[184:187], v[160:163], v[52:55]
	v_mfma_f32_16x16x32_bf16 v[36:39], v[184:187], v[168:171], v[36:39]
	v_mfma_f32_16x16x32_bf16 v[32:35], v[192:195], v[168:171], v[32:35]
	v_mfma_f32_16x16x32_bf16 v[16:19], v[192:195], v[176:179], v[16:19]
	v_mfma_f32_16x16x32_bf16 v[20:23], v[184:187], v[176:179], v[20:23]
	v_mfma_f32_16x16x32_bf16 v[68:71], v[188:191], v[156:159], v[68:71]
	v_mfma_f32_16x16x32_bf16 v[64:67], v[196:199], v[156:159], v[64:67]
	v_mfma_f32_16x16x32_bf16 v[48:51], v[196:199], v[164:167], v[48:51]
	v_mfma_f32_16x16x32_bf16 v[52:55], v[188:191], v[164:167], v[52:55]
	v_mfma_f32_16x16x32_bf16 v[36:39], v[188:191], v[172:175], v[36:39]
	v_mfma_f32_16x16x32_bf16 v[32:35], v[196:199], v[172:175], v[32:35]
	v_mfma_f32_16x16x32_bf16 v[16:19], v[196:199], v[180:183], v[16:19]
	v_mfma_f32_16x16x32_bf16 v[20:23], v[188:191], v[180:183], v[20:23]
	s_setprio 0
	s_setprio 1
	v_mfma_f32_16x16x32_bf16 v[60:63], v[208:211], v[150:153], v[60:63]
	v_mfma_f32_16x16x32_bf16 v[56:59], v[216:219], v[150:153], v[56:59]
	v_mfma_f32_16x16x32_bf16 v[40:43], v[216:219], v[160:163], v[40:43]
	v_mfma_f32_16x16x32_bf16 v[44:47], v[208:211], v[160:163], v[44:47]
	v_mfma_f32_16x16x32_bf16 v[28:31], v[208:211], v[168:171], v[28:31]
	v_mfma_f32_16x16x32_bf16 v[24:27], v[216:219], v[168:171], v[24:27]
	v_mfma_f32_16x16x32_bf16 v[8:11], v[216:219], v[176:179], v[8:11]
	v_mfma_f32_16x16x32_bf16 v[12:15], v[208:211], v[176:179], v[12:15]
	v_mfma_f32_16x16x32_bf16 v[60:63], v[212:215], v[156:159], v[60:63]
	v_mfma_f32_16x16x32_bf16 v[56:59], v[220:223], v[156:159], v[56:59]
	v_mfma_f32_16x16x32_bf16 v[40:43], v[220:223], v[164:167], v[40:43]
	v_mfma_f32_16x16x32_bf16 v[44:47], v[212:215], v[164:167], v[44:47]
	v_mfma_f32_16x16x32_bf16 v[28:31], v[212:215], v[172:175], v[28:31]
	v_mfma_f32_16x16x32_bf16 v[24:27], v[220:223], v[172:175], v[24:27]
	v_mfma_f32_16x16x32_bf16 v[8:11], v[220:223], v[180:183], v[8:11]
	v_mfma_f32_16x16x32_bf16 v[12:15], v[212:215], v[180:183], v[12:15]
	s_setprio 0
	s_barrier
	s_add_i32 s50, s50, 2
	s_add_u32 s44, s44, 0x100
	s_addc_u32 s45, s45, 0
	s_add_u32 s33, s33, 0x100
	s_addc_u32 s43, s43, 0
	s_cmp_gt_u32 s50, 29
	s_cbranch_scc0 .LBB0_986
	s_and_b64 vcc, exec, s[10:11]
	s_cbranch_vccz .LBB0_1031
	s_barrier
	s_cmp_gt_i32 s35, 15
	s_mov_b64 s[12:13], -1
	s_cbranch_scc1 .LBB0_1032

.LBB0_1482:
	s_add_i32 s26, s12, 2
	s_cmp_eq_u32 s57, s12
	s_cselect_b32 s13, s43, s51
	s_cselect_b32 s12, s42, s50
	s_cselect_b32 s65, s45, s15
	s_cselect_b32 s64, s44, s14
	s_add_i32 s27, 0, 0x10000
	s_movk_i32 s66, 0xff80
	v_add_u32_e32 v121, s27, v7
	s_add_i32 s63, 0, 0x14000
	v_lshl_add_u64 v[178:179], s[50:51], 0, v[108:109]
	s_mov_b32 s67, -1
	ds_read_b128 v[110:113], v119
	ds_read_b128 v[114:117], v119 offset:1024
	ds_read_b128 v[122:125], v119 offset:2048
	ds_read_b128 v[126:129], v119 offset:3072
	ds_read_b128 v[130:133], v119 offset:4096
	ds_read_b128 v[134:137], v119 offset:5120
	ds_read_b128 v[138:141], v119 offset:6144
	ds_read_b128 v[142:145], v119 offset:7168
	ds_read_b128 v[146:149], v121
	ds_read_b128 v[150:153], v121 offset:1024
	ds_read_b128 v[154:157], v121 offset:2048
	ds_read_b128 v[158:161], v121 offset:3072
	v_add_u32_e32 v121, s63, v7
	v_lshl_add_u64 v[178:179], v[178:179], 0, s[66:67]
	s_add_i32 m0, s39, 0xc000
	ds_read_b128 v[162:165], v121
	ds_read_b128 v[166:169], v121 offset:1024
	ds_read_b128 v[170:173], v121 offset:2048
	ds_read_b128 v[174:177], v121 offset:3072
	global_load_lds_dwordx4 v[178:179], off
	s_waitcnt vmcnt(7)
	s_waitcnt lgkmcnt(0)
	s_barrier
	s_setprio 1
	s_waitcnt lgkmcnt(0)
	v_mfma_f32_16x16x32_bf16 v[100:103], v[146:149], v[110:113], v[100:103]
	v_mfma_f32_16x16x32_bf16 v[96:99], v[154:157], v[110:113], v[96:99]
	v_mfma_f32_16x16x32_bf16 v[80:83], v[154:157], v[122:125], v[80:83]
	v_mfma_f32_16x16x32_bf16 v[92:95], v[146:149], v[122:125], v[92:95]
	v_mfma_f32_16x16x32_bf16 v[72:75], v[146:149], v[130:133], v[72:75]
	v_mfma_f32_16x16x32_bf16 v[64:67], v[154:157], v[130:133], v[64:67]
	v_mfma_f32_16x16x32_bf16 v[48:51], v[154:157], v[138:141], v[48:51]
	v_mfma_f32_16x16x32_bf16 v[56:59], v[146:149], v[138:141], v[56:59]
	v_mfma_f32_16x16x32_bf16 v[100:103], v[150:153], v[114:117], v[100:103]
	v_mfma_f32_16x16x32_bf16 v[96:99], v[158:161], v[114:117], v[96:99]
	v_mfma_f32_16x16x32_bf16 v[80:83], v[158:161], v[126:129], v[80:83]
	v_mfma_f32_16x16x32_bf16 v[92:95], v[150:153], v[126:129], v[92:95]
	v_mfma_f32_16x16x32_bf16 v[72:75], v[150:153], v[134:137], v[72:75]
	v_mfma_f32_16x16x32_bf16 v[64:67], v[158:161], v[134:137], v[64:67]
	v_mfma_f32_16x16x32_bf16 v[48:51], v[158:161], v[142:145], v[48:51]
	v_mfma_f32_16x16x32_bf16 v[56:59], v[150:153], v[142:145], v[56:59]
	s_setprio 0
	s_setprio 1
	v_mfma_f32_16x16x32_bf16 v[88:91], v[162:165], v[110:113], v[88:91]
	v_mfma_f32_16x16x32_bf16 v[84:87], v[170:173], v[110:113], v[84:87]
	v_mfma_f32_16x16x32_bf16 v[68:71], v[170:173], v[122:125], v[68:71]
	v_mfma_f32_16x16x32_bf16 v[76:79], v[162:165], v[122:125], v[76:79]
	v_mfma_f32_16x16x32_bf16 v[60:63], v[162:165], v[130:133], v[60:63]
	v_mfma_f32_16x16x32_bf16 v[52:55], v[170:173], v[130:133], v[52:55]
	v_mfma_f32_16x16x32_bf16 v[40:43], v[170:173], v[138:141], v[40:43]
	v_mfma_f32_16x16x32_bf16 v[44:47], v[162:165], v[138:141], v[44:47]
	v_mfma_f32_16x16x32_bf16 v[88:91], v[166:169], v[114:117], v[88:91]
	v_mfma_f32_16x16x32_bf16 v[84:87], v[174:177], v[114:117], v[84:87]
	v_mfma_f32_16x16x32_bf16 v[68:71], v[174:177], v[126:129], v[68:71]
	v_mfma_f32_16x16x32_bf16 v[76:79], v[166:169], v[126:129], v[76:79]
	v_mfma_f32_16x16x32_bf16 v[60:63], v[166:169], v[134:137], v[60:63]
	v_mfma_f32_16x16x32_bf16 v[52:55], v[174:177], v[134:137], v[52:55]
	v_mfma_f32_16x16x32_bf16 v[40:43], v[174:177], v[142:145], v[40:43]
	v_mfma_f32_16x16x32_bf16 v[44:47], v[166:169], v[142:145], v[44:47]
	s_setprio 0
	s_barrier
	s_add_i32 s27, s27, s22
	v_lshl_add_u64 v[178:179], s[64:65], 0, v[2:3]
	s_mov_b32 m0, s27
	ds_read_b128 v[110:113], v120 offset:16384
	ds_read_b128 v[114:117], v120 offset:17408
	ds_read_b128 v[122:125], v120 offset:18432
	ds_read_b128 v[126:129], v120 offset:19456
	global_load_lds_dwordx4 v[178:179], off
	s_add_i32 m0, s27, 0x2000
	v_lshl_add_u64 v[180:181], s[64:65], 0, v[4:5]
	s_add_u32 s64, s64, s90
	s_addc_u32 s65, s65, 0
	s_add_i32 s27, s63, s22
	global_load_lds_dwordx4 v[180:181], off
	v_lshl_add_u64 v[182:183], s[64:65], 0, v[2:3]
	s_mov_b32 m0, s27
	v_lshl_add_u64 v[184:185], s[64:65], 0, v[4:5]
	global_load_lds_dwordx4 v[182:183], off
	s_add_i32 m0, s27, 0x2000
	v_lshl_add_u64 v[186:187], s[12:13], 0, v[106:107]
	global_load_lds_dwordx4 v[184:185], off
	s_mov_b32 m0, s39
	v_lshl_add_u64 v[188:189], s[12:13], 0, v[104:105]
	global_load_lds_dwordx4 v[186:187], off
	s_mov_b32 m0, s40
	s_nop 0
	global_load_lds_dwordx4 v[188:189], off
	s_waitcnt vmcnt(7)
	s_waitcnt lgkmcnt(0)
	s_barrier
	s_setprio 1
	s_waitcnt lgkmcnt(0)
	v_mfma_f32_16x16x32_bf16 v[36:39], v[146:149], v[110:113], v[36:39]
	v_mfma_f32_16x16x32_bf16 v[32:35], v[154:157], v[110:113], v[32:35]
	v_mfma_f32_16x16x32_bf16 v[20:23], v[146:149], v[122:125], v[20:23]
	v_mfma_f32_16x16x32_bf16 v[16:19], v[154:157], v[122:125], v[16:19]
	v_mfma_f32_16x16x32_bf16 v[36:39], v[150:153], v[114:117], v[36:39]
	v_mfma_f32_16x16x32_bf16 v[32:35], v[158:161], v[114:117], v[32:35]
	v_mfma_f32_16x16x32_bf16 v[20:23], v[150:153], v[126:129], v[20:23]
	v_mfma_f32_16x16x32_bf16 v[16:19], v[158:161], v[126:129], v[16:19]
	s_setprio 0
	s_setprio 1
	v_mfma_f32_16x16x32_bf16 v[28:31], v[162:165], v[110:113], v[28:31]
	v_mfma_f32_16x16x32_bf16 v[24:27], v[170:173], v[110:113], v[24:27]
	v_mfma_f32_16x16x32_bf16 v[12:15], v[162:165], v[122:125], v[12:15]
	v_mfma_f32_16x16x32_bf16 v[8:11], v[170:173], v[122:125], v[8:11]
	v_mfma_f32_16x16x32_bf16 v[28:31], v[166:169], v[114:117], v[28:31]
	v_mfma_f32_16x16x32_bf16 v[24:27], v[174:177], v[114:117], v[24:27]
	v_mfma_f32_16x16x32_bf16 v[12:15], v[166:169], v[126:129], v[12:15]
	v_mfma_f32_16x16x32_bf16 v[8:11], v[174:177], v[126:129], v[8:11]
	s_setprio 0
	s_barrier
	s_add_i32 s27, 0, 0x18000
	s_add_i32 s63, 0, 0x1c000
	s_add_u32 s12, s12, s90
	v_add_u32_e32 v121, s27, v7
	s_addc_u32 s13, s13, 0
	ds_read_b128 v[110:113], v119 offset:32768
	ds_read_b128 v[114:117], v119 offset:33792
	ds_read_b128 v[122:125], v119 offset:34816
	ds_read_b128 v[126:129], v119 offset:35840
	ds_read_b128 v[130:133], v119 offset:36864
	ds_read_b128 v[134:137], v119 offset:37888
	ds_read_b128 v[138:141], v119 offset:38912
	ds_read_b128 v[142:145], v119 offset:39936
	ds_read_b128 v[146:149], v121
	ds_read_b128 v[150:153], v121 offset:1024
	ds_read_b128 v[154:157], v121 offset:2048
	ds_read_b128 v[158:161], v121 offset:3072
	v_add_u32_e32 v121, s63, v7
	v_lshl_add_u64 v[190:191], s[12:13], 0, v[106:107]
	s_mov_b32 m0, s41
	ds_read_b128 v[162:165], v121
	ds_read_b128 v[166:169], v121 offset:1024
	ds_read_b128 v[170:173], v121 offset:2048
	ds_read_b128 v[174:177], v121 offset:3072
	global_load_lds_dwordx4 v[190:191], off
	s_waitcnt vmcnt(7)
	s_waitcnt lgkmcnt(0)
	s_barrier
	s_setprio 1
	s_waitcnt lgkmcnt(0)
	v_mfma_f32_16x16x32_bf16 v[100:103], v[146:149], v[110:113], v[100:103]
	v_mfma_f32_16x16x32_bf16 v[96:99], v[154:157], v[110:113], v[96:99]
	v_mfma_f32_16x16x32_bf16 v[80:83], v[154:157], v[122:125], v[80:83]
	v_mfma_f32_16x16x32_bf16 v[92:95], v[146:149], v[122:125], v[92:95]
	v_mfma_f32_16x16x32_bf16 v[72:75], v[146:149], v[130:133], v[72:75]
	v_mfma_f32_16x16x32_bf16 v[64:67], v[154:157], v[130:133], v[64:67]
	v_mfma_f32_16x16x32_bf16 v[48:51], v[154:157], v[138:141], v[48:51]
	v_mfma_f32_16x16x32_bf16 v[56:59], v[146:149], v[138:141], v[56:59]
	v_mfma_f32_16x16x32_bf16 v[100:103], v[150:153], v[114:117], v[100:103]
	v_mfma_f32_16x16x32_bf16 v[96:99], v[158:161], v[114:117], v[96:99]
	v_mfma_f32_16x16x32_bf16 v[80:83], v[158:161], v[126:129], v[80:83]
	v_mfma_f32_16x16x32_bf16 v[92:95], v[150:153], v[126:129], v[92:95]
	v_mfma_f32_16x16x32_bf16 v[72:75], v[150:153], v[134:137], v[72:75]
	v_mfma_f32_16x16x32_bf16 v[64:67], v[158:161], v[134:137], v[64:67]
	v_mfma_f32_16x16x32_bf16 v[48:51], v[158:161], v[142:145], v[48:51]
	v_mfma_f32_16x16x32_bf16 v[56:59], v[150:153], v[142:145], v[56:59]
	s_setprio 0
	s_setprio 1
	v_mfma_f32_16x16x32_bf16 v[88:91], v[162:165], v[110:113], v[88:91]
	v_mfma_f32_16x16x32_bf16 v[84:87], v[170:173], v[110:113], v[84:87]
	v_mfma_f32_16x16x32_bf16 v[68:71], v[170:173], v[122:125], v[68:71]
	v_mfma_f32_16x16x32_bf16 v[76:79], v[162:165], v[122:125], v[76:79]
	v_mfma_f32_16x16x32_bf16 v[60:63], v[162:165], v[130:133], v[60:63]
	v_mfma_f32_16x16x32_bf16 v[52:55], v[170:173], v[130:133], v[52:55]
	v_mfma_f32_16x16x32_bf16 v[40:43], v[170:173], v[138:141], v[40:43]
	v_mfma_f32_16x16x32_bf16 v[44:47], v[162:165], v[138:141], v[44:47]
	v_mfma_f32_16x16x32_bf16 v[88:91], v[166:169], v[114:117], v[88:91]
	v_mfma_f32_16x16x32_bf16 v[84:87], v[174:177], v[114:117], v[84:87]
	v_mfma_f32_16x16x32_bf16 v[68:71], v[174:177], v[126:129], v[68:71]
	v_mfma_f32_16x16x32_bf16 v[76:79], v[166:169], v[126:129], v[76:79]
	v_mfma_f32_16x16x32_bf16 v[60:63], v[166:169], v[134:137], v[60:63]
	v_mfma_f32_16x16x32_bf16 v[52:55], v[174:177], v[134:137], v[52:55]
	v_mfma_f32_16x16x32_bf16 v[40:43], v[174:177], v[142:145], v[40:43]
	v_mfma_f32_16x16x32_bf16 v[44:47], v[166:169], v[142:145], v[44:47]
	s_setprio 0
	s_barrier
	s_add_i32 s12, s27, s22
	v_lshl_add_u64 v[130:131], v[178:179], 0, s[0:1]
	s_mov_b32 m0, s12
	ds_read_b128 v[110:113], v120 offset:49152
	ds_read_b128 v[114:117], v120 offset:50176
	ds_read_b128 v[122:125], v120 offset:51200
	ds_read_b128 v[126:129], v120 offset:52224
	global_load_lds_dwordx4 v[130:131], off
	v_lshl_add_u64 v[130:131], v[180:181], 0, s[0:1]
	s_add_i32 m0, s12, 0x2000
	s_add_i32 s12, s63, s22
	global_load_lds_dwordx4 v[130:131], off
	v_lshl_add_u64 v[130:131], v[182:183], 0, s[0:1]
	s_mov_b32 m0, s12
	s_nop 0
	global_load_lds_dwordx4 v[130:131], off
	v_lshl_add_u64 v[130:131], v[184:185], 0, s[0:1]
	s_add_i32 m0, s12, 0x2000
	s_nop 0
	global_load_lds_dwordx4 v[130:131], off
	v_lshl_add_u64 v[130:131], v[186:187], 0, s[0:1]
	s_mov_b32 m0, s53
	s_nop 0
	global_load_lds_dwordx4 v[130:131], off
	v_lshl_add_u64 v[130:131], v[188:189], 0, s[0:1]
	s_mov_b32 m0, s54
	s_nop 0
	global_load_lds_dwordx4 v[130:131], off
	s_waitcnt vmcnt(7)
	s_waitcnt lgkmcnt(0)
	s_barrier
	s_setprio 1
	s_waitcnt lgkmcnt(0)
	v_mfma_f32_16x16x32_bf16 v[36:39], v[146:149], v[110:113], v[36:39]
	v_mfma_f32_16x16x32_bf16 v[32:35], v[154:157], v[110:113], v[32:35]
	v_mfma_f32_16x16x32_bf16 v[20:23], v[146:149], v[122:125], v[20:23]
	v_mfma_f32_16x16x32_bf16 v[16:19], v[154:157], v[122:125], v[16:19]
	v_mfma_f32_16x16x32_bf16 v[36:39], v[150:153], v[114:117], v[36:39]
	v_mfma_f32_16x16x32_bf16 v[32:35], v[158:161], v[114:117], v[32:35]
	v_mfma_f32_16x16x32_bf16 v[20:23], v[150:153], v[126:129], v[20:23]
	v_mfma_f32_16x16x32_bf16 v[16:19], v[158:161], v[126:129], v[16:19]
	s_setprio 0
	s_setprio 1
	v_mfma_f32_16x16x32_bf16 v[28:31], v[162:165], v[110:113], v[28:31]
	v_mfma_f32_16x16x32_bf16 v[24:27], v[170:173], v[110:113], v[24:27]
	v_mfma_f32_16x16x32_bf16 v[12:15], v[162:165], v[122:125], v[12:15]
	v_mfma_f32_16x16x32_bf16 v[8:11], v[170:173], v[122:125], v[8:11]
	v_mfma_f32_16x16x32_bf16 v[28:31], v[166:169], v[114:117], v[28:31]
	v_mfma_f32_16x16x32_bf16 v[24:27], v[174:177], v[114:117], v[24:27]
	v_mfma_f32_16x16x32_bf16 v[12:15], v[166:169], v[126:129], v[12:15]
	v_mfma_f32_16x16x32_bf16 v[8:11], v[174:177], v[126:129], v[8:11]
	s_setprio 0
	s_barrier
	s_add_u32 s50, s50, 0x100
	s_addc_u32 s51, s51, 0
	s_add_u32 s14, s14, 0x100
	s_addc_u32 s15, s15, 0
	s_cmp_ge_u32 s26, s55
	s_mov_b32 s12, s26
	s_cbranch_scc0 .LBB0_1482
	s_and_b64 vcc, exec, s[36:37]
	s_cbranch_vccz .LBB0_1485
	s_barrier
